# GEMM MFMA block: priority dropped 4 MFMAs before the block's end so the wave is already at priority 0 when the closing barrier releases
# baseline (speedup 1.0000x reference)
.Lrx_G_IN_0:
	s_waitcnt vmcnt(16)
	s_waitcnt lgkmcnt(0)
	s_setprio 1
	s_barrier
	v_mfma_f32_16x16x32_bf16 v[126:129], v[130:133], v[188:191], v[126:129]
	v_mfma_f32_16x16x32_bf16 v[122:125], v[164:167], v[188:191], v[122:125]
	v_mfma_f32_16x16x32_bf16 v[110:113], v[130:133], v[196:199], v[110:113]
	v_mfma_f32_16x16x32_bf16 v[106:109], v[164:167], v[196:199], v[106:109]
	v_mfma_f32_16x16x32_bf16 v[92:95], v[130:133], v[214:217], v[92:95]
	v_mfma_f32_16x16x32_bf16 v[88:91], v[164:167], v[214:217], v[88:91]
	v_mfma_f32_16x16x32_bf16 v[76:79], v[130:133], v[222:225], v[76:79]
	v_mfma_f32_16x16x32_bf16 v[72:75], v[164:167], v[222:225], v[72:75]
	v_mfma_f32_16x16x32_bf16 v[126:129], v[160:163], v[192:195], v[126:129]
	v_mfma_f32_16x16x32_bf16 v[122:125], v[168:171], v[192:195], v[122:125]
	v_mfma_f32_16x16x32_bf16 v[110:113], v[160:163], v[210:213], v[110:113]
	v_mfma_f32_16x16x32_bf16 v[106:109], v[168:171], v[210:213], v[106:109]
	v_mfma_f32_16x16x32_bf16 v[92:95], v[160:163], v[218:221], v[92:95]
	v_mfma_f32_16x16x32_bf16 v[88:91], v[168:171], v[218:221], v[88:91]
	v_mfma_f32_16x16x32_bf16 v[76:79], v[160:163], v[226:229], v[76:79]
	v_mfma_f32_16x16x32_bf16 v[72:75], v[168:171], v[226:229], v[72:75]
	v_mfma_f32_16x16x32_bf16 v[118:121], v[172:175], v[188:191], v[118:121]
	v_mfma_f32_16x16x32_bf16 v[114:117], v[180:183], v[188:191], v[114:117]
	v_mfma_f32_16x16x32_bf16 v[102:105], v[172:175], v[196:199], v[102:105]
	v_mfma_f32_16x16x32_bf16 v[98:101], v[180:183], v[196:199], v[98:101]
	v_mfma_f32_16x16x32_bf16 v[84:87], v[172:175], v[214:217], v[84:87]
	v_mfma_f32_16x16x32_bf16 v[80:83], v[180:183], v[214:217], v[80:83]
	v_mfma_f32_16x16x32_bf16 v[68:71], v[172:175], v[222:225], v[68:71]
	v_mfma_f32_16x16x32_bf16 v[64:67], v[180:183], v[222:225], v[64:67]
	v_mfma_f32_16x16x32_bf16 v[118:121], v[176:179], v[192:195], v[118:121]
	v_mfma_f32_16x16x32_bf16 v[114:117], v[184:187], v[192:195], v[114:117]
	v_mfma_f32_16x16x32_bf16 v[102:105], v[176:179], v[210:213], v[102:105]
	v_mfma_f32_16x16x32_bf16 v[98:101], v[184:187], v[210:213], v[98:101]
	s_setprio 0
	v_mfma_f32_16x16x32_bf16 v[84:87], v[176:179], v[218:221], v[84:87]
	v_mfma_f32_16x16x32_bf16 v[80:83], v[184:187], v[218:221], v[80:83]
	v_mfma_f32_16x16x32_bf16 v[68:71], v[176:179], v[226:229], v[68:71]
	v_mfma_f32_16x16x32_bf16 v[64:67], v[184:187], v[226:229], v[64:67]
	s_barrier
	s_add_i32 s55, s55, s75
	v_lshl_add_u64 v[150:151], s[44:45], 0, v[142:143]
	s_mov_b32 m0, s55
	ds_read_b128 v[188:191], v159 offset:16384
	ds_read_b128 v[192:195], v159 offset:17408
	ds_read_b128 v[196:199], v159 offset:18432
	ds_read_b128 v[210:213], v159 offset:19456
	ds_read_b128 v[214:217], v159 offset:20480
	ds_read_b128 v[218:221], v159 offset:21504
	ds_read_b128 v[222:225], v159 offset:22528
	ds_read_b128 v[226:229], v159 offset:23552
	global_load_lds_dwordx4 v[150:151], off
	s_add_i32 m0, s55, 0x2000
	s_add_u32 s56, s44, 0x80000
	v_lshl_add_u64 v[154:155], s[44:45], 0, v[138:139]
	s_addc_u32 s57, s45, 0
	s_add_i32 s55, s61, s75
	global_load_lds_dwordx4 v[154:155], off
	v_lshl_add_u64 v[156:157], s[56:57], 0, v[142:143]
	s_mov_b32 m0, s55
	v_lshl_add_u64 v[202:203], s[52:53], 0, v[140:141]
	global_load_lds_dwordx4 v[156:157], off
	v_lshl_add_u64 v[156:157], s[56:57], 0, v[138:139]
	s_add_i32 m0, s55, 0x2000
	s_nop 0
	global_load_lds_dwordx4 v[156:157], off
	v_lshl_add_u64 v[156:157], s[52:53], 0, v[144:145]
	s_mov_b32 m0, s35
	s_nop 0
	global_load_lds_dwordx4 v[156:157], off
	s_mov_b32 m0, s68
	s_nop 0
	global_load_lds_dwordx4 v[202:203], off
	v_cmp_ne_u32_e32 vcc, 0, v243
	s_cbranch_vccnz .Lrx_G_IN_1
	s_waitcnt vmcnt(8)
.Lrx_G_IN_1:
	s_waitcnt vmcnt(16)
	v_mov_b32_e32 v243, 0
	s_waitcnt lgkmcnt(0)
	s_setprio 1
	s_barrier
	v_mfma_f32_16x16x32_bf16 v[60:63], v[130:133], v[188:191], v[60:63]
	v_mfma_f32_16x16x32_bf16 v[56:59], v[164:167], v[188:191], v[56:59]
	v_mfma_f32_16x16x32_bf16 v[44:47], v[130:133], v[196:199], v[44:47]
	v_mfma_f32_16x16x32_bf16 v[40:43], v[164:167], v[196:199], v[40:43]
	v_mfma_f32_16x16x32_bf16 v[28:31], v[130:133], v[214:217], v[28:31]
	v_mfma_f32_16x16x32_bf16 v[24:27], v[164:167], v[214:217], v[24:27]
	v_mfma_f32_16x16x32_bf16 v[12:15], v[130:133], v[222:225], v[12:15]
	v_mfma_f32_16x16x32_bf16 v[8:11], v[164:167], v[222:225], v[8:11]
	v_mfma_f32_16x16x32_bf16 v[60:63], v[160:163], v[192:195], v[60:63]
	v_mfma_f32_16x16x32_bf16 v[56:59], v[168:171], v[192:195], v[56:59]
	v_mfma_f32_16x16x32_bf16 v[44:47], v[160:163], v[210:213], v[44:47]
	v_mfma_f32_16x16x32_bf16 v[40:43], v[168:171], v[210:213], v[40:43]
	v_mfma_f32_16x16x32_bf16 v[28:31], v[160:163], v[218:221], v[28:31]
	v_mfma_f32_16x16x32_bf16 v[24:27], v[168:171], v[218:221], v[24:27]
	v_mfma_f32_16x16x32_bf16 v[12:15], v[160:163], v[226:229], v[12:15]
	v_mfma_f32_16x16x32_bf16 v[8:11], v[168:171], v[226:229], v[8:11]
	v_mfma_f32_16x16x32_bf16 v[52:55], v[172:175], v[188:191], v[52:55]
	v_mfma_f32_16x16x32_bf16 v[48:51], v[180:183], v[188:191], v[48:51]
	v_mfma_f32_16x16x32_bf16 v[36:39], v[172:175], v[196:199], v[36:39]
	v_mfma_f32_16x16x32_bf16 v[32:35], v[180:183], v[196:199], v[32:35]
	v_mfma_f32_16x16x32_bf16 v[20:23], v[172:175], v[214:217], v[20:23]
	v_mfma_f32_16x16x32_bf16 v[16:19], v[180:183], v[214:217], v[16:19]
	v_mfma_f32_16x16x32_bf16 v[4:7], v[172:175], v[222:225], v[4:7]
	v_mfma_f32_16x16x32_bf16 v[0:3], v[180:183], v[222:225], v[0:3]
	v_mfma_f32_16x16x32_bf16 v[52:55], v[176:179], v[192:195], v[52:55]
	v_mfma_f32_16x16x32_bf16 v[48:51], v[184:187], v[192:195], v[48:51]
	v_mfma_f32_16x16x32_bf16 v[36:39], v[176:179], v[210:213], v[36:39]
	v_mfma_f32_16x16x32_bf16 v[32:35], v[184:187], v[210:213], v[32:35]
	s_setprio 0
	v_mfma_f32_16x16x32_bf16 v[20:23], v[176:179], v[218:221], v[20:23]
	v_mfma_f32_16x16x32_bf16 v[16:19], v[184:187], v[218:221], v[16:19]
	v_mfma_f32_16x16x32_bf16 v[4:7], v[176:179], v[226:229], v[4:7]
	v_mfma_f32_16x16x32_bf16 v[0:3], v[184:187], v[226:229], v[0:3]
	s_barrier
	s_add_i32 s55, 0, 0x18000
	s_add_i32 s56, 0, 0x1c000
	v_add_u32_e32 v168, s55, v158
	v_add_u32_e32 v184, s56, v158
	ds_read_b128 v[130:133], v168
	ds_read_b128 v[160:163], v168 offset:1024
	ds_read_b128 v[164:167], v168 offset:2048
	ds_read_b128 v[168:171], v168 offset:3072
	ds_read_b128 v[172:175], v184
	ds_read_b128 v[176:179], v184 offset:1024
	ds_read_b128 v[180:183], v184 offset:2048
	ds_read_b128 v[184:187], v184 offset:3072
	s_add_u32 s52, s52, 0x80000
	s_addc_u32 s53, s53, 0
	s_mov_b32 m0, s69
	v_lshl_add_u64 v[204:205], s[52:53], 0, v[144:145]
	ds_read_b128 v[188:191], v159 offset:32768
	ds_read_b128 v[192:195], v159 offset:33792
	ds_read_b128 v[196:199], v159 offset:34816
	ds_read_b128 v[210:213], v159 offset:35840
	ds_read_b128 v[214:217], v159 offset:36864
	ds_read_b128 v[218:221], v159 offset:37888
	ds_read_b128 v[222:225], v159 offset:38912
	ds_read_b128 v[226:229], v159 offset:39936
	global_load_lds_dwordx4 v[204:205], off
	v_lshl_add_u64 v[204:205], s[52:53], 0, v[140:141]
	s_mov_b32 m0, s77
	s_nop 0
	global_load_lds_dwordx4 v[204:205], off
	s_waitcnt vmcnt(8)
	s_waitcnt lgkmcnt(0)
	s_setprio 1
	s_barrier
	v_mfma_f32_16x16x32_bf16 v[126:129], v[130:133], v[188:191], v[126:129]
	v_mfma_f32_16x16x32_bf16 v[122:125], v[164:167], v[188:191], v[122:125]
	v_mfma_f32_16x16x32_bf16 v[110:113], v[130:133], v[196:199], v[110:113]
	v_mfma_f32_16x16x32_bf16 v[106:109], v[164:167], v[196:199], v[106:109]
	v_mfma_f32_16x16x32_bf16 v[92:95], v[130:133], v[214:217], v[92:95]
	v_mfma_f32_16x16x32_bf16 v[88:91], v[164:167], v[214:217], v[88:91]
	v_mfma_f32_16x16x32_bf16 v[76:79], v[130:133], v[222:225], v[76:79]
	v_mfma_f32_16x16x32_bf16 v[72:75], v[164:167], v[222:225], v[72:75]
	v_mfma_f32_16x16x32_bf16 v[126:129], v[160:163], v[192:195], v[126:129]
	v_mfma_f32_16x16x32_bf16 v[122:125], v[168:171], v[192:195], v[122:125]
	v_mfma_f32_16x16x32_bf16 v[110:113], v[160:163], v[210:213], v[110:113]
	v_mfma_f32_16x16x32_bf16 v[106:109], v[168:171], v[210:213], v[106:109]
	v_mfma_f32_16x16x32_bf16 v[92:95], v[160:163], v[218:221], v[92:95]
	v_mfma_f32_16x16x32_bf16 v[88:91], v[168:171], v[218:221], v[88:91]
	v_mfma_f32_16x16x32_bf16 v[76:79], v[160:163], v[226:229], v[76:79]
	v_mfma_f32_16x16x32_bf16 v[72:75], v[168:171], v[226:229], v[72:75]
	v_mfma_f32_16x16x32_bf16 v[118:121], v[172:175], v[188:191], v[118:121]
	v_mfma_f32_16x16x32_bf16 v[114:117], v[180:183], v[188:191], v[114:117]
	v_mfma_f32_16x16x32_bf16 v[102:105], v[172:175], v[196:199], v[102:105]
	v_mfma_f32_16x16x32_bf16 v[98:101], v[180:183], v[196:199], v[98:101]
	v_mfma_f32_16x16x32_bf16 v[84:87], v[172:175], v[214:217], v[84:87]
	v_mfma_f32_16x16x32_bf16 v[80:83], v[180:183], v[214:217], v[80:83]
	v_mfma_f32_16x16x32_bf16 v[68:71], v[172:175], v[222:225], v[68:71]
	v_mfma_f32_16x16x32_bf16 v[64:67], v[180:183], v[222:225], v[64:67]
	v_mfma_f32_16x16x32_bf16 v[118:121], v[176:179], v[192:195], v[118:121]
	v_mfma_f32_16x16x32_bf16 v[114:117], v[184:187], v[192:195], v[114:117]
	v_mfma_f32_16x16x32_bf16 v[102:105], v[176:179], v[210:213], v[102:105]
	v_mfma_f32_16x16x32_bf16 v[98:101], v[184:187], v[210:213], v[98:101]
	s_setprio 0
	v_mfma_f32_16x16x32_bf16 v[84:87], v[176:179], v[218:221], v[84:87]
	v_mfma_f32_16x16x32_bf16 v[80:83], v[184:187], v[218:221], v[80:83]
	v_mfma_f32_16x16x32_bf16 v[68:71], v[176:179], v[226:229], v[68:71]
	v_mfma_f32_16x16x32_bf16 v[64:67], v[184:187], v[226:229], v[64:67]
	s_barrier
	s_add_i32 s52, s55, s75
	v_lshl_add_u64 v[150:151], v[150:151], 0, s[64:65]
	s_mov_b32 m0, s52
	ds_read_b128 v[188:191], v159 offset:49152
	ds_read_b128 v[192:195], v159 offset:50176
	ds_read_b128 v[196:199], v159 offset:51200
	ds_read_b128 v[210:213], v159 offset:52224
	ds_read_b128 v[214:217], v159 offset:53248
	ds_read_b128 v[218:221], v159 offset:54272
	ds_read_b128 v[222:225], v159 offset:55296
	ds_read_b128 v[226:229], v159 offset:56320
	global_load_lds_dwordx4 v[150:151], off
	s_add_i32 m0, s52, 0x2000
	s_add_u32 s44, s44, 0x80080
	v_lshl_add_u64 v[150:151], v[154:155], 0, s[64:65]
	s_addc_u32 s45, s45, 0
	s_add_i32 s52, s56, s75
	global_load_lds_dwordx4 v[150:151], off
	v_lshl_add_u64 v[150:151], s[44:45], 0, v[142:143]
	s_mov_b32 m0, s52
	s_nop 0
	global_load_lds_dwordx4 v[150:151], off
	v_lshl_add_u64 v[150:151], s[44:45], 0, v[138:139]
	s_add_i32 m0, s52, 0x2000
	s_nop 0
	global_load_lds_dwordx4 v[150:151], off
	v_lshl_add_u64 v[150:151], v[156:157], 0, s[64:65]
	s_mov_b32 m0, s79
	s_nop 0
	global_load_lds_dwordx4 v[150:151], off
	v_lshl_add_u64 v[150:151], v[202:203], 0, s[64:65]
	s_mov_b32 m0, s81
	s_nop 0
	global_load_lds_dwordx4 v[150:151], off
	s_waitcnt vmcnt(8)
	s_waitcnt lgkmcnt(0)
	s_setprio 1
	s_barrier
	v_mfma_f32_16x16x32_bf16 v[60:63], v[130:133], v[188:191], v[60:63]
	v_mfma_f32_16x16x32_bf16 v[56:59], v[164:167], v[188:191], v[56:59]
	v_mfma_f32_16x16x32_bf16 v[44:47], v[130:133], v[196:199], v[44:47]
	v_mfma_f32_16x16x32_bf16 v[40:43], v[164:167], v[196:199], v[40:43]
	v_mfma_f32_16x16x32_bf16 v[28:31], v[130:133], v[214:217], v[28:31]
	v_mfma_f32_16x16x32_bf16 v[24:27], v[164:167], v[214:217], v[24:27]
	v_mfma_f32_16x16x32_bf16 v[12:15], v[130:133], v[222:225], v[12:15]
	v_mfma_f32_16x16x32_bf16 v[8:11], v[164:167], v[222:225], v[8:11]
	v_mfma_f32_16x16x32_bf16 v[60:63], v[160:163], v[192:195], v[60:63]
	v_mfma_f32_16x16x32_bf16 v[56:59], v[168:171], v[192:195], v[56:59]
	v_mfma_f32_16x16x32_bf16 v[44:47], v[160:163], v[210:213], v[44:47]
	v_mfma_f32_16x16x32_bf16 v[40:43], v[168:171], v[210:213], v[40:43]
	v_mfma_f32_16x16x32_bf16 v[28:31], v[160:163], v[218:221], v[28:31]
	v_mfma_f32_16x16x32_bf16 v[24:27], v[168:171], v[218:221], v[24:27]
	v_mfma_f32_16x16x32_bf16 v[12:15], v[160:163], v[226:229], v[12:15]
	v_mfma_f32_16x16x32_bf16 v[8:11], v[168:171], v[226:229], v[8:11]
	v_mfma_f32_16x16x32_bf16 v[52:55], v[172:175], v[188:191], v[52:55]
	v_mfma_f32_16x16x32_bf16 v[48:51], v[180:183], v[188:191], v[48:51]
	v_mfma_f32_16x16x32_bf16 v[36:39], v[172:175], v[196:199], v[36:39]
	v_mfma_f32_16x16x32_bf16 v[32:35], v[180:183], v[196:199], v[32:35]
	v_mfma_f32_16x16x32_bf16 v[20:23], v[172:175], v[214:217], v[20:23]
	v_mfma_f32_16x16x32_bf16 v[16:19], v[180:183], v[214:217], v[16:19]
	v_mfma_f32_16x16x32_bf16 v[4:7], v[172:175], v[222:225], v[4:7]
	v_mfma_f32_16x16x32_bf16 v[0:3], v[180:183], v[222:225], v[0:3]
	v_mfma_f32_16x16x32_bf16 v[52:55], v[176:179], v[192:195], v[52:55]
	v_mfma_f32_16x16x32_bf16 v[48:51], v[184:187], v[192:195], v[48:51]
	v_mfma_f32_16x16x32_bf16 v[36:39], v[176:179], v[210:213], v[36:39]
	v_mfma_f32_16x16x32_bf16 v[32:35], v[184:187], v[210:213], v[32:35]
	s_setprio 0
	v_mfma_f32_16x16x32_bf16 v[20:23], v[176:179], v[218:221], v[20:23]
	v_mfma_f32_16x16x32_bf16 v[16:19], v[184:187], v[218:221], v[16:19]
	v_mfma_f32_16x16x32_bf16 v[4:7], v[176:179], v[226:229], v[4:7]
	v_mfma_f32_16x16x32_bf16 v[0:3], v[184:187], v[226:229], v[0:3]
	s_barrier
	s_add_i32 s54, s54, 2
	s_add_u32 s42, s42, 0x100
	s_addc_u32 s43, s43, 0
	s_add_u32 s28, s28, 0x100
	s_addc_u32 s33, s33, 0
	s_cmp_gt_u32 s54, 29
	s_cbranch_scc0 .LBB0_352
	v_mov_b32_e32 v243, 1
	v_readlane_b32 s6, v251, 54
	v_readlane_b32 s7, v251, 55
	s_and_b64 vcc, exec, s[6:7]
	s_cbranch_vccz .LBB0_355
	s_barrier

.Lrx_uq_0:
	s_waitcnt vmcnt(24)
	s_waitcnt lgkmcnt(0)
	s_setprio 1
	s_barrier
	v_mfma_f32_16x16x32_bf16 v[126:129], v[146:149], v[182:185], v[126:129]
	v_mfma_f32_16x16x32_bf16 v[122:125], v[158:161], v[182:185], v[122:125]
	v_mfma_f32_16x16x32_bf16 v[118:121], v[146:149], v[190:193], v[118:121]
	v_mfma_f32_16x16x32_bf16 v[114:117], v[158:161], v[190:193], v[114:117]
	v_mfma_f32_16x16x32_bf16 v[102:105], v[146:149], v[210:213], v[102:105]
	v_mfma_f32_16x16x32_bf16 v[98:101], v[158:161], v[210:213], v[98:101]
	v_mfma_f32_16x16x32_bf16 v[84:87], v[146:149], v[218:221], v[84:87]
	v_mfma_f32_16x16x32_bf16 v[80:83], v[158:161], v[218:221], v[80:83]
	v_mfma_f32_16x16x32_bf16 v[126:129], v[150:153], v[186:189], v[126:129]
	v_mfma_f32_16x16x32_bf16 v[122:125], v[162:165], v[186:189], v[122:125]
	v_mfma_f32_16x16x32_bf16 v[118:121], v[150:153], v[194:197], v[118:121]
	v_mfma_f32_16x16x32_bf16 v[114:117], v[162:165], v[194:197], v[114:117]
	v_mfma_f32_16x16x32_bf16 v[102:105], v[150:153], v[214:217], v[102:105]
	v_mfma_f32_16x16x32_bf16 v[98:101], v[162:165], v[214:217], v[98:101]
	v_mfma_f32_16x16x32_bf16 v[84:87], v[150:153], v[222:225], v[84:87]
	v_mfma_f32_16x16x32_bf16 v[80:83], v[162:165], v[222:225], v[80:83]
	v_mfma_f32_16x16x32_bf16 v[110:113], v[166:169], v[182:185], v[110:113]
	v_mfma_f32_16x16x32_bf16 v[106:109], v[174:177], v[182:185], v[106:109]
	v_mfma_f32_16x16x32_bf16 v[92:95], v[166:169], v[190:193], v[92:95]
	v_mfma_f32_16x16x32_bf16 v[88:91], v[174:177], v[190:193], v[88:91]
	v_mfma_f32_16x16x32_bf16 v[76:79], v[166:169], v[210:213], v[76:79]
	v_mfma_f32_16x16x32_bf16 v[72:75], v[174:177], v[210:213], v[72:75]
	v_mfma_f32_16x16x32_bf16 v[68:71], v[166:169], v[218:221], v[68:71]
	v_mfma_f32_16x16x32_bf16 v[64:67], v[174:177], v[218:221], v[64:67]
	v_mfma_f32_16x16x32_bf16 v[110:113], v[170:173], v[186:189], v[110:113]
	v_mfma_f32_16x16x32_bf16 v[106:109], v[178:181], v[186:189], v[106:109]
	v_mfma_f32_16x16x32_bf16 v[92:95], v[170:173], v[194:197], v[92:95]
	v_mfma_f32_16x16x32_bf16 v[88:91], v[178:181], v[194:197], v[88:91]
	s_setprio 0
	v_mfma_f32_16x16x32_bf16 v[76:79], v[170:173], v[214:217], v[76:79]
	v_mfma_f32_16x16x32_bf16 v[72:75], v[178:181], v[214:217], v[72:75]
	v_mfma_f32_16x16x32_bf16 v[68:71], v[170:173], v[222:225], v[68:71]
	v_mfma_f32_16x16x32_bf16 v[64:67], v[178:181], v[222:225], v[64:67]
	s_barrier
	s_add_i32 s56, s58, s75
	v_lshl_add_u64 v[154:155], s[82:83], 0, v[96:97]
	s_mov_b32 m0, s56
	ds_read_b128 v[182:185], v144 offset:16384
	ds_read_b128 v[186:189], v144 offset:17408
	ds_read_b128 v[190:193], v144 offset:18432
	ds_read_b128 v[194:197], v144 offset:19456
	ds_read_b128 v[210:213], v144 offset:20480
	ds_read_b128 v[214:217], v144 offset:21504
	ds_read_b128 v[218:221], v144 offset:22528
	ds_read_b128 v[222:225], v144 offset:23552
	global_load_lds_dwordx4 v[154:155], off
	s_add_i32 m0, s56, 0x2000
	s_add_u32 s56, s82, 0x20000
	v_lshl_add_u64 v[156:157], s[82:83], 0, v[130:131]
	s_addc_u32 s57, s83, 0
	s_add_i32 s58, s59, s75
	global_load_lds_dwordx4 v[156:157], off
	v_lshl_add_u64 v[198:199], s[56:57], 0, v[96:97]
	s_mov_b32 m0, s58
	v_lshl_add_u64 v[202:203], s[84:85], 0, v[132:133]
	global_load_lds_dwordx4 v[198:199], off
	v_lshl_add_u64 v[198:199], s[56:57], 0, v[130:131]
	s_add_i32 m0, s58, 0x2000
	s_nop 0
	global_load_lds_dwordx4 v[198:199], off
	v_lshl_add_u64 v[198:199], s[84:85], 0, v[134:135]
	s_mov_b32 m0, s10
	s_nop 0
	global_load_lds_dwordx4 v[198:199], off
	s_mov_b32 m0, s12
	s_nop 0
	global_load_lds_dwordx4 v[202:203], off
	v_cmp_ne_u32_e32 vcc, 0, v243
	s_cbranch_vccnz .Lrx_uq_1
	s_waitcnt vmcnt(8)
.Lrx_uq_1:
	s_waitcnt vmcnt(24)
	v_mov_b32_e32 v243, 0
	s_waitcnt lgkmcnt(0)
	s_setprio 1
	s_barrier
	v_mfma_f32_16x16x32_bf16 v[60:63], v[146:149], v[182:185], v[60:63]
	v_mfma_f32_16x16x32_bf16 v[56:59], v[158:161], v[182:185], v[56:59]
	v_mfma_f32_16x16x32_bf16 v[52:55], v[146:149], v[190:193], v[52:55]
	v_mfma_f32_16x16x32_bf16 v[48:51], v[158:161], v[190:193], v[48:51]
	v_mfma_f32_16x16x32_bf16 v[36:39], v[146:149], v[210:213], v[36:39]
	v_mfma_f32_16x16x32_bf16 v[32:35], v[158:161], v[210:213], v[32:35]
	v_mfma_f32_16x16x32_bf16 v[20:23], v[146:149], v[218:221], v[20:23]
	v_mfma_f32_16x16x32_bf16 v[16:19], v[158:161], v[218:221], v[16:19]
	v_mfma_f32_16x16x32_bf16 v[60:63], v[150:153], v[186:189], v[60:63]
	v_mfma_f32_16x16x32_bf16 v[56:59], v[162:165], v[186:189], v[56:59]
	v_mfma_f32_16x16x32_bf16 v[52:55], v[150:153], v[194:197], v[52:55]
	v_mfma_f32_16x16x32_bf16 v[48:51], v[162:165], v[194:197], v[48:51]
	v_mfma_f32_16x16x32_bf16 v[36:39], v[150:153], v[214:217], v[36:39]
	v_mfma_f32_16x16x32_bf16 v[32:35], v[162:165], v[214:217], v[32:35]
	v_mfma_f32_16x16x32_bf16 v[20:23], v[150:153], v[222:225], v[20:23]
	v_mfma_f32_16x16x32_bf16 v[16:19], v[162:165], v[222:225], v[16:19]
	v_mfma_f32_16x16x32_bf16 v[44:47], v[166:169], v[182:185], v[44:47]
	v_mfma_f32_16x16x32_bf16 v[40:43], v[174:177], v[182:185], v[40:43]
	v_mfma_f32_16x16x32_bf16 v[28:31], v[166:169], v[190:193], v[28:31]
	v_mfma_f32_16x16x32_bf16 v[24:27], v[174:177], v[190:193], v[24:27]
	v_mfma_f32_16x16x32_bf16 v[12:15], v[166:169], v[210:213], v[12:15]
	v_mfma_f32_16x16x32_bf16 v[8:11], v[174:177], v[210:213], v[8:11]
	v_mfma_f32_16x16x32_bf16 v[4:7], v[166:169], v[218:221], v[4:7]
	v_mfma_f32_16x16x32_bf16 v[0:3], v[174:177], v[218:221], v[0:3]
	v_mfma_f32_16x16x32_bf16 v[44:47], v[170:173], v[186:189], v[44:47]
	v_mfma_f32_16x16x32_bf16 v[40:43], v[178:181], v[186:189], v[40:43]
	v_mfma_f32_16x16x32_bf16 v[28:31], v[170:173], v[194:197], v[28:31]
	v_mfma_f32_16x16x32_bf16 v[24:27], v[178:181], v[194:197], v[24:27]
	s_setprio 0
	v_mfma_f32_16x16x32_bf16 v[12:15], v[170:173], v[214:217], v[12:15]
	v_mfma_f32_16x16x32_bf16 v[8:11], v[178:181], v[214:217], v[8:11]
	v_mfma_f32_16x16x32_bf16 v[4:7], v[170:173], v[222:225], v[4:7]
	v_mfma_f32_16x16x32_bf16 v[0:3], v[178:181], v[222:225], v[0:3]
	s_barrier
	s_add_i32 s58, 0, 0x18000
	v_add_u32_e32 v145, s58, v142
	s_add_i32 s59, 0, 0x1c000
	ds_read_b128 v[146:149], v145
	ds_read_b128 v[150:153], v145 offset:1024
	ds_read_b128 v[158:161], v145 offset:2048
	ds_read_b128 v[162:165], v145 offset:3072
	v_add_u32_e32 v145, s59, v142
	ds_read_b128 v[166:169], v145
	ds_read_b128 v[170:173], v145 offset:1024
	ds_read_b128 v[174:177], v145 offset:2048
	ds_read_b128 v[178:181], v145 offset:3072
	s_add_u32 s56, s84, 0x20000
	s_addc_u32 s57, s85, 0
	s_mov_b32 m0, s18
	v_lshl_add_u64 v[204:205], s[56:57], 0, v[134:135]
	ds_read_b128 v[182:185], v144 offset:32768
	ds_read_b128 v[186:189], v144 offset:33792
	ds_read_b128 v[190:193], v144 offset:34816
	ds_read_b128 v[194:197], v144 offset:35840
	ds_read_b128 v[210:213], v144 offset:36864
	ds_read_b128 v[214:217], v144 offset:37888
	ds_read_b128 v[218:221], v144 offset:38912
	ds_read_b128 v[222:225], v144 offset:39936
	global_load_lds_dwordx4 v[204:205], off
	v_lshl_add_u64 v[204:205], s[56:57], 0, v[132:133]
	s_mov_b32 m0, s20
	s_nop 0
	global_load_lds_dwordx4 v[204:205], off
	s_waitcnt vmcnt(8)
	s_waitcnt lgkmcnt(0)
	s_setprio 1
	s_barrier
	v_mfma_f32_16x16x32_bf16 v[126:129], v[146:149], v[182:185], v[126:129]
	v_mfma_f32_16x16x32_bf16 v[122:125], v[158:161], v[182:185], v[122:125]
	v_mfma_f32_16x16x32_bf16 v[118:121], v[146:149], v[190:193], v[118:121]
	v_mfma_f32_16x16x32_bf16 v[114:117], v[158:161], v[190:193], v[114:117]
	v_mfma_f32_16x16x32_bf16 v[102:105], v[146:149], v[210:213], v[102:105]
	v_mfma_f32_16x16x32_bf16 v[98:101], v[158:161], v[210:213], v[98:101]
	v_mfma_f32_16x16x32_bf16 v[84:87], v[146:149], v[218:221], v[84:87]
	v_mfma_f32_16x16x32_bf16 v[80:83], v[158:161], v[218:221], v[80:83]
	v_mfma_f32_16x16x32_bf16 v[126:129], v[150:153], v[186:189], v[126:129]
	v_mfma_f32_16x16x32_bf16 v[122:125], v[162:165], v[186:189], v[122:125]
	v_mfma_f32_16x16x32_bf16 v[118:121], v[150:153], v[194:197], v[118:121]
	v_mfma_f32_16x16x32_bf16 v[114:117], v[162:165], v[194:197], v[114:117]
	v_mfma_f32_16x16x32_bf16 v[102:105], v[150:153], v[214:217], v[102:105]
	v_mfma_f32_16x16x32_bf16 v[98:101], v[162:165], v[214:217], v[98:101]
	v_mfma_f32_16x16x32_bf16 v[84:87], v[150:153], v[222:225], v[84:87]
	v_mfma_f32_16x16x32_bf16 v[80:83], v[162:165], v[222:225], v[80:83]
	v_mfma_f32_16x16x32_bf16 v[110:113], v[166:169], v[182:185], v[110:113]
	v_mfma_f32_16x16x32_bf16 v[106:109], v[174:177], v[182:185], v[106:109]
	v_mfma_f32_16x16x32_bf16 v[92:95], v[166:169], v[190:193], v[92:95]
	v_mfma_f32_16x16x32_bf16 v[88:91], v[174:177], v[190:193], v[88:91]
	v_mfma_f32_16x16x32_bf16 v[76:79], v[166:169], v[210:213], v[76:79]
	v_mfma_f32_16x16x32_bf16 v[72:75], v[174:177], v[210:213], v[72:75]
	v_mfma_f32_16x16x32_bf16 v[68:71], v[166:169], v[218:221], v[68:71]
	v_mfma_f32_16x16x32_bf16 v[64:67], v[174:177], v[218:221], v[64:67]
	v_mfma_f32_16x16x32_bf16 v[110:113], v[170:173], v[186:189], v[110:113]
	v_mfma_f32_16x16x32_bf16 v[106:109], v[178:181], v[186:189], v[106:109]
	v_mfma_f32_16x16x32_bf16 v[92:95], v[170:173], v[194:197], v[92:95]
	v_mfma_f32_16x16x32_bf16 v[88:91], v[178:181], v[194:197], v[88:91]
	s_setprio 0
	v_mfma_f32_16x16x32_bf16 v[76:79], v[170:173], v[214:217], v[76:79]
	v_mfma_f32_16x16x32_bf16 v[72:75], v[178:181], v[214:217], v[72:75]
	v_mfma_f32_16x16x32_bf16 v[68:71], v[170:173], v[222:225], v[68:71]
	v_mfma_f32_16x16x32_bf16 v[64:67], v[178:181], v[222:225], v[64:67]
	s_barrier
	s_add_i32 s56, s58, s75
	v_lshl_add_u64 v[154:155], v[154:155], 0, s[64:65]
	s_mov_b32 m0, s56
	ds_read_b128 v[182:185], v144 offset:49152
	ds_read_b128 v[186:189], v144 offset:50176
	ds_read_b128 v[190:193], v144 offset:51200
	ds_read_b128 v[194:197], v144 offset:52224
	ds_read_b128 v[210:213], v144 offset:53248
	ds_read_b128 v[214:217], v144 offset:54272
	ds_read_b128 v[218:221], v144 offset:55296
	ds_read_b128 v[222:225], v144 offset:56320
	global_load_lds_dwordx4 v[154:155], off
	s_add_i32 m0, s56, 0x2000
	s_add_u32 s56, s82, 0x20080
	v_lshl_add_u64 v[154:155], v[156:157], 0, s[64:65]
	s_addc_u32 s57, s83, 0
	s_add_i32 s58, s59, s75
	global_load_lds_dwordx4 v[154:155], off
	v_lshl_add_u64 v[154:155], s[56:57], 0, v[96:97]
	s_mov_b32 m0, s58
	s_nop 0
	global_load_lds_dwordx4 v[154:155], off
	v_lshl_add_u64 v[154:155], s[56:57], 0, v[130:131]
	s_add_i32 m0, s58, 0x2000
	s_nop 0
	global_load_lds_dwordx4 v[154:155], off
	v_lshl_add_u64 v[154:155], v[198:199], 0, s[64:65]
	s_mov_b32 m0, s26
	s_nop 0
	global_load_lds_dwordx4 v[154:155], off
	v_lshl_add_u64 v[154:155], v[202:203], 0, s[64:65]
	s_mov_b32 m0, s27
	s_nop 0
	global_load_lds_dwordx4 v[154:155], off
	s_waitcnt vmcnt(8)
	s_waitcnt lgkmcnt(0)
	s_setprio 1
	s_barrier
	v_mfma_f32_16x16x32_bf16 v[60:63], v[146:149], v[182:185], v[60:63]
	v_mfma_f32_16x16x32_bf16 v[56:59], v[158:161], v[182:185], v[56:59]
	v_mfma_f32_16x16x32_bf16 v[52:55], v[146:149], v[190:193], v[52:55]
	v_mfma_f32_16x16x32_bf16 v[48:51], v[158:161], v[190:193], v[48:51]
	v_mfma_f32_16x16x32_bf16 v[36:39], v[146:149], v[210:213], v[36:39]
	v_mfma_f32_16x16x32_bf16 v[32:35], v[158:161], v[210:213], v[32:35]
	v_mfma_f32_16x16x32_bf16 v[20:23], v[146:149], v[218:221], v[20:23]
	v_mfma_f32_16x16x32_bf16 v[16:19], v[158:161], v[218:221], v[16:19]
	v_mfma_f32_16x16x32_bf16 v[60:63], v[150:153], v[186:189], v[60:63]
	v_mfma_f32_16x16x32_bf16 v[56:59], v[162:165], v[186:189], v[56:59]
	v_mfma_f32_16x16x32_bf16 v[52:55], v[150:153], v[194:197], v[52:55]
	v_mfma_f32_16x16x32_bf16 v[48:51], v[162:165], v[194:197], v[48:51]
	v_mfma_f32_16x16x32_bf16 v[36:39], v[150:153], v[214:217], v[36:39]
	v_mfma_f32_16x16x32_bf16 v[32:35], v[162:165], v[214:217], v[32:35]
	v_mfma_f32_16x16x32_bf16 v[20:23], v[150:153], v[222:225], v[20:23]
	v_mfma_f32_16x16x32_bf16 v[16:19], v[162:165], v[222:225], v[16:19]
	v_mfma_f32_16x16x32_bf16 v[44:47], v[166:169], v[182:185], v[44:47]
	v_mfma_f32_16x16x32_bf16 v[40:43], v[174:177], v[182:185], v[40:43]
	v_mfma_f32_16x16x32_bf16 v[28:31], v[166:169], v[190:193], v[28:31]
	v_mfma_f32_16x16x32_bf16 v[24:27], v[174:177], v[190:193], v[24:27]
	v_mfma_f32_16x16x32_bf16 v[12:15], v[166:169], v[210:213], v[12:15]
	v_mfma_f32_16x16x32_bf16 v[8:11], v[174:177], v[210:213], v[8:11]
	v_mfma_f32_16x16x32_bf16 v[4:7], v[166:169], v[218:221], v[4:7]
	v_mfma_f32_16x16x32_bf16 v[0:3], v[174:177], v[218:221], v[0:3]
	v_mfma_f32_16x16x32_bf16 v[44:47], v[170:173], v[186:189], v[44:47]
	v_mfma_f32_16x16x32_bf16 v[40:43], v[178:181], v[186:189], v[40:43]
	v_mfma_f32_16x16x32_bf16 v[28:31], v[170:173], v[194:197], v[28:31]
	v_mfma_f32_16x16x32_bf16 v[24:27], v[178:181], v[194:197], v[24:27]
	s_setprio 0
	v_mfma_f32_16x16x32_bf16 v[12:15], v[170:173], v[214:217], v[12:15]
	v_mfma_f32_16x16x32_bf16 v[8:11], v[178:181], v[214:217], v[8:11]
	v_mfma_f32_16x16x32_bf16 v[4:7], v[170:173], v[222:225], v[4:7]
	v_mfma_f32_16x16x32_bf16 v[0:3], v[178:181], v[222:225], v[0:3]
	s_barrier
	s_add_i32 s55, s55, 2
	s_add_u32 s68, s68, 0x100
	s_addc_u32 s69, s69, 0
	s_add_u32 s51, s51, 0x100
	s_addc_u32 s54, s54, 0
	s_cmp_gt_u32 s55, 5
	s_cbranch_scc0 .LBB0_636
	v_mov_b32_e32 v243, 1
	v_readlane_b32 s6, v251, 54
	v_readlane_b32 s7, v251, 55
	s_and_b64 vcc, exec, s[6:7]
	s_cbranch_vccz .LBB0_639
	s_barrier

.Lrx_ukv_0:
	s_waitcnt vmcnt(24)
	s_waitcnt lgkmcnt(0)
	s_setprio 1
	s_barrier
	v_mfma_f32_16x16x32_bf16 v[126:129], v[146:149], v[182:185], v[126:129]
	v_mfma_f32_16x16x32_bf16 v[122:125], v[158:161], v[182:185], v[122:125]
	v_mfma_f32_16x16x32_bf16 v[118:121], v[146:149], v[190:193], v[118:121]
	v_mfma_f32_16x16x32_bf16 v[114:117], v[158:161], v[190:193], v[114:117]
	v_mfma_f32_16x16x32_bf16 v[102:105], v[146:149], v[210:213], v[102:105]
	v_mfma_f32_16x16x32_bf16 v[98:101], v[158:161], v[210:213], v[98:101]
	v_mfma_f32_16x16x32_bf16 v[84:87], v[146:149], v[218:221], v[84:87]
	v_mfma_f32_16x16x32_bf16 v[80:83], v[158:161], v[218:221], v[80:83]
	v_mfma_f32_16x16x32_bf16 v[126:129], v[150:153], v[186:189], v[126:129]
	v_mfma_f32_16x16x32_bf16 v[122:125], v[162:165], v[186:189], v[122:125]
	v_mfma_f32_16x16x32_bf16 v[118:121], v[150:153], v[194:197], v[118:121]
	v_mfma_f32_16x16x32_bf16 v[114:117], v[162:165], v[194:197], v[114:117]
	v_mfma_f32_16x16x32_bf16 v[102:105], v[150:153], v[214:217], v[102:105]
	v_mfma_f32_16x16x32_bf16 v[98:101], v[162:165], v[214:217], v[98:101]
	v_mfma_f32_16x16x32_bf16 v[84:87], v[150:153], v[222:225], v[84:87]
	v_mfma_f32_16x16x32_bf16 v[80:83], v[162:165], v[222:225], v[80:83]
	v_mfma_f32_16x16x32_bf16 v[110:113], v[166:169], v[182:185], v[110:113]
	v_mfma_f32_16x16x32_bf16 v[106:109], v[174:177], v[182:185], v[106:109]
	v_mfma_f32_16x16x32_bf16 v[92:95], v[166:169], v[190:193], v[92:95]
	v_mfma_f32_16x16x32_bf16 v[88:91], v[174:177], v[190:193], v[88:91]
	v_mfma_f32_16x16x32_bf16 v[76:79], v[166:169], v[210:213], v[76:79]
	v_mfma_f32_16x16x32_bf16 v[72:75], v[174:177], v[210:213], v[72:75]
	v_mfma_f32_16x16x32_bf16 v[68:71], v[166:169], v[218:221], v[68:71]
	v_mfma_f32_16x16x32_bf16 v[64:67], v[174:177], v[218:221], v[64:67]
	v_mfma_f32_16x16x32_bf16 v[110:113], v[170:173], v[186:189], v[110:113]
	v_mfma_f32_16x16x32_bf16 v[106:109], v[178:181], v[186:189], v[106:109]
	v_mfma_f32_16x16x32_bf16 v[92:95], v[170:173], v[194:197], v[92:95]
	v_mfma_f32_16x16x32_bf16 v[88:91], v[178:181], v[194:197], v[88:91]
	s_setprio 0
	v_mfma_f32_16x16x32_bf16 v[76:79], v[170:173], v[214:217], v[76:79]
	v_mfma_f32_16x16x32_bf16 v[72:75], v[178:181], v[214:217], v[72:75]
	v_mfma_f32_16x16x32_bf16 v[68:71], v[170:173], v[222:225], v[68:71]
	v_mfma_f32_16x16x32_bf16 v[64:67], v[178:181], v[222:225], v[64:67]
	s_barrier
	s_add_i32 s58, s61, s75
	v_lshl_add_u64 v[154:155], s[82:83], 0, v[96:97]
	s_mov_b32 m0, s58
	ds_read_b128 v[182:185], v144 offset:16384
	ds_read_b128 v[186:189], v144 offset:17408
	ds_read_b128 v[190:193], v144 offset:18432
	ds_read_b128 v[194:197], v144 offset:19456
	ds_read_b128 v[210:213], v144 offset:20480
	ds_read_b128 v[214:217], v144 offset:21504
	ds_read_b128 v[218:221], v144 offset:22528
	ds_read_b128 v[222:225], v144 offset:23552
	global_load_lds_dwordx4 v[154:155], off
	s_add_i32 m0, s58, 0x2000
	s_add_u32 s58, s82, 0x20000
	v_lshl_add_u64 v[156:157], s[82:83], 0, v[130:131]
	s_addc_u32 s59, s83, 0
	s_add_i32 s61, s62, s75
	global_load_lds_dwordx4 v[156:157], off
	v_lshl_add_u64 v[198:199], s[58:59], 0, v[96:97]
	s_mov_b32 m0, s61
	v_lshl_add_u64 v[202:203], s[84:85], 0, v[132:133]
	global_load_lds_dwordx4 v[198:199], off
	v_lshl_add_u64 v[198:199], s[58:59], 0, v[130:131]
	s_add_i32 m0, s61, 0x2000
	s_nop 0
	global_load_lds_dwordx4 v[198:199], off
	v_lshl_add_u64 v[198:199], s[84:85], 0, v[134:135]
	s_mov_b32 m0, s18
	s_nop 0
	global_load_lds_dwordx4 v[198:199], off
	s_mov_b32 m0, s20
	s_nop 0
	global_load_lds_dwordx4 v[202:203], off
	v_cmp_ne_u32_e32 vcc, 0, v243
	s_cbranch_vccnz .Lrx_ukv_1
	s_waitcnt vmcnt(8)
.Lrx_ukv_1:
	s_waitcnt vmcnt(24)
	v_mov_b32_e32 v243, 0
	s_waitcnt lgkmcnt(0)
	s_setprio 1
	s_barrier
	v_mfma_f32_16x16x32_bf16 v[60:63], v[146:149], v[182:185], v[60:63]
	v_mfma_f32_16x16x32_bf16 v[56:59], v[158:161], v[182:185], v[56:59]
	v_mfma_f32_16x16x32_bf16 v[52:55], v[146:149], v[190:193], v[52:55]
	v_mfma_f32_16x16x32_bf16 v[48:51], v[158:161], v[190:193], v[48:51]
	v_mfma_f32_16x16x32_bf16 v[36:39], v[146:149], v[210:213], v[36:39]
	v_mfma_f32_16x16x32_bf16 v[32:35], v[158:161], v[210:213], v[32:35]
	v_mfma_f32_16x16x32_bf16 v[20:23], v[146:149], v[218:221], v[20:23]
	v_mfma_f32_16x16x32_bf16 v[16:19], v[158:161], v[218:221], v[16:19]
	v_mfma_f32_16x16x32_bf16 v[60:63], v[150:153], v[186:189], v[60:63]
	v_mfma_f32_16x16x32_bf16 v[56:59], v[162:165], v[186:189], v[56:59]
	v_mfma_f32_16x16x32_bf16 v[52:55], v[150:153], v[194:197], v[52:55]
	v_mfma_f32_16x16x32_bf16 v[48:51], v[162:165], v[194:197], v[48:51]
	v_mfma_f32_16x16x32_bf16 v[36:39], v[150:153], v[214:217], v[36:39]
	v_mfma_f32_16x16x32_bf16 v[32:35], v[162:165], v[214:217], v[32:35]
	v_mfma_f32_16x16x32_bf16 v[20:23], v[150:153], v[222:225], v[20:23]
	v_mfma_f32_16x16x32_bf16 v[16:19], v[162:165], v[222:225], v[16:19]
	v_mfma_f32_16x16x32_bf16 v[44:47], v[166:169], v[182:185], v[44:47]
	v_mfma_f32_16x16x32_bf16 v[40:43], v[174:177], v[182:185], v[40:43]
	v_mfma_f32_16x16x32_bf16 v[28:31], v[166:169], v[190:193], v[28:31]
	v_mfma_f32_16x16x32_bf16 v[24:27], v[174:177], v[190:193], v[24:27]
	v_mfma_f32_16x16x32_bf16 v[12:15], v[166:169], v[210:213], v[12:15]
	v_mfma_f32_16x16x32_bf16 v[8:11], v[174:177], v[210:213], v[8:11]
	v_mfma_f32_16x16x32_bf16 v[4:7], v[166:169], v[218:221], v[4:7]
	v_mfma_f32_16x16x32_bf16 v[0:3], v[174:177], v[218:221], v[0:3]
	v_mfma_f32_16x16x32_bf16 v[44:47], v[170:173], v[186:189], v[44:47]
	v_mfma_f32_16x16x32_bf16 v[40:43], v[178:181], v[186:189], v[40:43]
	v_mfma_f32_16x16x32_bf16 v[28:31], v[170:173], v[194:197], v[28:31]
	v_mfma_f32_16x16x32_bf16 v[24:27], v[178:181], v[194:197], v[24:27]
	s_setprio 0
	v_mfma_f32_16x16x32_bf16 v[12:15], v[170:173], v[214:217], v[12:15]
	v_mfma_f32_16x16x32_bf16 v[8:11], v[178:181], v[214:217], v[8:11]
	v_mfma_f32_16x16x32_bf16 v[4:7], v[170:173], v[222:225], v[4:7]
	v_mfma_f32_16x16x32_bf16 v[0:3], v[178:181], v[222:225], v[0:3]
	s_barrier
	s_add_i32 s61, 0, 0x18000
	v_add_u32_e32 v145, s61, v142
	s_add_i32 s62, 0, 0x1c000
	ds_read_b128 v[146:149], v145
	ds_read_b128 v[150:153], v145 offset:1024
	ds_read_b128 v[158:161], v145 offset:2048
	ds_read_b128 v[162:165], v145 offset:3072
	v_add_u32_e32 v145, s62, v142
	ds_read_b128 v[166:169], v145
	ds_read_b128 v[170:173], v145 offset:1024
	ds_read_b128 v[174:177], v145 offset:2048
	ds_read_b128 v[178:181], v145 offset:3072
	s_add_u32 s58, s84, 0x20000
	s_addc_u32 s59, s85, 0
	s_mov_b32 m0, s26
	v_lshl_add_u64 v[204:205], s[58:59], 0, v[134:135]
	ds_read_b128 v[182:185], v144 offset:32768
	ds_read_b128 v[186:189], v144 offset:33792
	ds_read_b128 v[190:193], v144 offset:34816
	ds_read_b128 v[194:197], v144 offset:35840
	ds_read_b128 v[210:213], v144 offset:36864
	ds_read_b128 v[214:217], v144 offset:37888
	ds_read_b128 v[218:221], v144 offset:38912
	ds_read_b128 v[222:225], v144 offset:39936
	global_load_lds_dwordx4 v[204:205], off
	v_lshl_add_u64 v[204:205], s[58:59], 0, v[132:133]
	s_mov_b32 m0, s27
	s_nop 0
	global_load_lds_dwordx4 v[204:205], off
	s_waitcnt vmcnt(8)
	s_waitcnt lgkmcnt(0)
	s_setprio 1
	s_barrier
	v_mfma_f32_16x16x32_bf16 v[126:129], v[146:149], v[182:185], v[126:129]
	v_mfma_f32_16x16x32_bf16 v[122:125], v[158:161], v[182:185], v[122:125]
	v_mfma_f32_16x16x32_bf16 v[118:121], v[146:149], v[190:193], v[118:121]
	v_mfma_f32_16x16x32_bf16 v[114:117], v[158:161], v[190:193], v[114:117]
	v_mfma_f32_16x16x32_bf16 v[102:105], v[146:149], v[210:213], v[102:105]
	v_mfma_f32_16x16x32_bf16 v[98:101], v[158:161], v[210:213], v[98:101]
	v_mfma_f32_16x16x32_bf16 v[84:87], v[146:149], v[218:221], v[84:87]
	v_mfma_f32_16x16x32_bf16 v[80:83], v[158:161], v[218:221], v[80:83]
	v_mfma_f32_16x16x32_bf16 v[126:129], v[150:153], v[186:189], v[126:129]
	v_mfma_f32_16x16x32_bf16 v[122:125], v[162:165], v[186:189], v[122:125]
	v_mfma_f32_16x16x32_bf16 v[118:121], v[150:153], v[194:197], v[118:121]
	v_mfma_f32_16x16x32_bf16 v[114:117], v[162:165], v[194:197], v[114:117]
	v_mfma_f32_16x16x32_bf16 v[102:105], v[150:153], v[214:217], v[102:105]
	v_mfma_f32_16x16x32_bf16 v[98:101], v[162:165], v[214:217], v[98:101]
	v_mfma_f32_16x16x32_bf16 v[84:87], v[150:153], v[222:225], v[84:87]
	v_mfma_f32_16x16x32_bf16 v[80:83], v[162:165], v[222:225], v[80:83]
	v_mfma_f32_16x16x32_bf16 v[110:113], v[166:169], v[182:185], v[110:113]
	v_mfma_f32_16x16x32_bf16 v[106:109], v[174:177], v[182:185], v[106:109]
	v_mfma_f32_16x16x32_bf16 v[92:95], v[166:169], v[190:193], v[92:95]
	v_mfma_f32_16x16x32_bf16 v[88:91], v[174:177], v[190:193], v[88:91]
	v_mfma_f32_16x16x32_bf16 v[76:79], v[166:169], v[210:213], v[76:79]
	v_mfma_f32_16x16x32_bf16 v[72:75], v[174:177], v[210:213], v[72:75]
	v_mfma_f32_16x16x32_bf16 v[68:71], v[166:169], v[218:221], v[68:71]
	v_mfma_f32_16x16x32_bf16 v[64:67], v[174:177], v[218:221], v[64:67]
	v_mfma_f32_16x16x32_bf16 v[110:113], v[170:173], v[186:189], v[110:113]
	v_mfma_f32_16x16x32_bf16 v[106:109], v[178:181], v[186:189], v[106:109]
	v_mfma_f32_16x16x32_bf16 v[92:95], v[170:173], v[194:197], v[92:95]
	v_mfma_f32_16x16x32_bf16 v[88:91], v[178:181], v[194:197], v[88:91]
	s_setprio 0
	v_mfma_f32_16x16x32_bf16 v[76:79], v[170:173], v[214:217], v[76:79]
	v_mfma_f32_16x16x32_bf16 v[72:75], v[178:181], v[214:217], v[72:75]
	v_mfma_f32_16x16x32_bf16 v[68:71], v[170:173], v[222:225], v[68:71]
	v_mfma_f32_16x16x32_bf16 v[64:67], v[178:181], v[222:225], v[64:67]
	s_barrier
	s_add_i32 s58, s61, s75
	v_lshl_add_u64 v[154:155], v[154:155], 0, s[64:65]
	s_mov_b32 m0, s58
	ds_read_b128 v[182:185], v144 offset:49152
	ds_read_b128 v[186:189], v144 offset:50176
	ds_read_b128 v[190:193], v144 offset:51200
	ds_read_b128 v[194:197], v144 offset:52224
	ds_read_b128 v[210:213], v144 offset:53248
	ds_read_b128 v[214:217], v144 offset:54272
	ds_read_b128 v[218:221], v144 offset:55296
	ds_read_b128 v[222:225], v144 offset:56320
	global_load_lds_dwordx4 v[154:155], off
	s_add_i32 m0, s58, 0x2000
	s_add_u32 s58, s82, 0x20080
	v_lshl_add_u64 v[154:155], v[156:157], 0, s[64:65]
	s_addc_u32 s59, s83, 0
	s_add_i32 s61, s62, s75
	global_load_lds_dwordx4 v[154:155], off
	v_lshl_add_u64 v[154:155], s[58:59], 0, v[96:97]
	s_mov_b32 m0, s61
	s_nop 0
	global_load_lds_dwordx4 v[154:155], off
	v_lshl_add_u64 v[154:155], s[58:59], 0, v[130:131]
	s_add_i32 m0, s61, 0x2000
	s_nop 0
	global_load_lds_dwordx4 v[154:155], off
	v_lshl_add_u64 v[154:155], v[198:199], 0, s[64:65]
	s_mov_b32 m0, s28
	s_nop 0
	global_load_lds_dwordx4 v[154:155], off
	v_lshl_add_u64 v[154:155], v[202:203], 0, s[64:65]
	s_mov_b32 m0, s33
	s_nop 0
	global_load_lds_dwordx4 v[154:155], off
	s_waitcnt vmcnt(8)
	s_waitcnt lgkmcnt(0)
	s_setprio 1
	s_barrier
	v_mfma_f32_16x16x32_bf16 v[60:63], v[146:149], v[182:185], v[60:63]
	v_mfma_f32_16x16x32_bf16 v[56:59], v[158:161], v[182:185], v[56:59]
	v_mfma_f32_16x16x32_bf16 v[52:55], v[146:149], v[190:193], v[52:55]
	v_mfma_f32_16x16x32_bf16 v[48:51], v[158:161], v[190:193], v[48:51]
	v_mfma_f32_16x16x32_bf16 v[36:39], v[146:149], v[210:213], v[36:39]
	v_mfma_f32_16x16x32_bf16 v[32:35], v[158:161], v[210:213], v[32:35]
	v_mfma_f32_16x16x32_bf16 v[20:23], v[146:149], v[218:221], v[20:23]
	v_mfma_f32_16x16x32_bf16 v[16:19], v[158:161], v[218:221], v[16:19]
	v_mfma_f32_16x16x32_bf16 v[60:63], v[150:153], v[186:189], v[60:63]
	v_mfma_f32_16x16x32_bf16 v[56:59], v[162:165], v[186:189], v[56:59]
	v_mfma_f32_16x16x32_bf16 v[52:55], v[150:153], v[194:197], v[52:55]
	v_mfma_f32_16x16x32_bf16 v[48:51], v[162:165], v[194:197], v[48:51]
	v_mfma_f32_16x16x32_bf16 v[36:39], v[150:153], v[214:217], v[36:39]
	v_mfma_f32_16x16x32_bf16 v[32:35], v[162:165], v[214:217], v[32:35]
	v_mfma_f32_16x16x32_bf16 v[20:23], v[150:153], v[222:225], v[20:23]
	v_mfma_f32_16x16x32_bf16 v[16:19], v[162:165], v[222:225], v[16:19]
	v_mfma_f32_16x16x32_bf16 v[44:47], v[166:169], v[182:185], v[44:47]
	v_mfma_f32_16x16x32_bf16 v[40:43], v[174:177], v[182:185], v[40:43]
	v_mfma_f32_16x16x32_bf16 v[28:31], v[166:169], v[190:193], v[28:31]
	v_mfma_f32_16x16x32_bf16 v[24:27], v[174:177], v[190:193], v[24:27]
	v_mfma_f32_16x16x32_bf16 v[12:15], v[166:169], v[210:213], v[12:15]
	v_mfma_f32_16x16x32_bf16 v[8:11], v[174:177], v[210:213], v[8:11]
	v_mfma_f32_16x16x32_bf16 v[4:7], v[166:169], v[218:221], v[4:7]
	v_mfma_f32_16x16x32_bf16 v[0:3], v[174:177], v[218:221], v[0:3]
	v_mfma_f32_16x16x32_bf16 v[44:47], v[170:173], v[186:189], v[44:47]
	v_mfma_f32_16x16x32_bf16 v[40:43], v[178:181], v[186:189], v[40:43]
	v_mfma_f32_16x16x32_bf16 v[28:31], v[170:173], v[194:197], v[28:31]
	v_mfma_f32_16x16x32_bf16 v[24:27], v[178:181], v[194:197], v[24:27]
	s_setprio 0
	v_mfma_f32_16x16x32_bf16 v[12:15], v[170:173], v[214:217], v[12:15]
	v_mfma_f32_16x16x32_bf16 v[8:11], v[178:181], v[214:217], v[8:11]
	v_mfma_f32_16x16x32_bf16 v[4:7], v[170:173], v[222:225], v[4:7]
	v_mfma_f32_16x16x32_bf16 v[0:3], v[178:181], v[222:225], v[0:3]
	s_barrier
	s_add_i32 s57, s57, 2
	s_add_u32 s68, s68, 0x100
	s_addc_u32 s69, s69, 0
	s_add_u32 s55, s55, 0x100
	s_addc_u32 s56, s56, 0
	s_cmp_gt_u32 s57, 5
	s_cbranch_scc0 .LBB0_656
	v_mov_b32_e32 v243, 1
	v_readlane_b32 s6, v251, 54
	v_readlane_b32 s7, v251, 55
	s_and_b64 vcc, exec, s[6:7]
	s_cbranch_vccz .LBB0_659
	s_barrier

.Lrx_G_OUT_0:
	s_waitcnt vmcnt(44)
	s_waitcnt lgkmcnt(0)
	s_setprio 1
	s_barrier
	v_mfma_f32_16x16x32_bf16 v[126:129], v[130:133], v[184:187], v[126:129]
	v_mfma_f32_16x16x32_bf16 v[122:125], v[152:155], v[184:187], v[122:125]
	v_mfma_f32_16x16x32_bf16 v[110:113], v[130:133], v[192:195], v[110:113]
	v_mfma_f32_16x16x32_bf16 v[106:109], v[152:155], v[192:195], v[106:109]
	v_mfma_f32_16x16x32_bf16 v[92:95], v[130:133], v[202:205], v[92:95]
	v_mfma_f32_16x16x32_bf16 v[88:91], v[152:155], v[202:205], v[88:91]
	v_mfma_f32_16x16x32_bf16 v[76:79], v[130:133], v[214:217], v[76:79]
	v_mfma_f32_16x16x32_bf16 v[72:75], v[152:155], v[214:217], v[72:75]
	v_mfma_f32_16x16x32_bf16 v[126:129], v[134:137], v[188:191], v[126:129]
	v_mfma_f32_16x16x32_bf16 v[122:125], v[156:159], v[188:191], v[122:125]
	v_mfma_f32_16x16x32_bf16 v[110:113], v[134:137], v[196:199], v[110:113]
	v_mfma_f32_16x16x32_bf16 v[106:109], v[156:159], v[196:199], v[106:109]
	v_mfma_f32_16x16x32_bf16 v[92:95], v[134:137], v[210:213], v[92:95]
	v_mfma_f32_16x16x32_bf16 v[88:91], v[156:159], v[210:213], v[88:91]
	v_mfma_f32_16x16x32_bf16 v[76:79], v[134:137], v[218:221], v[76:79]
	v_mfma_f32_16x16x32_bf16 v[72:75], v[156:159], v[218:221], v[72:75]
	v_mfma_f32_16x16x32_bf16 v[118:121], v[160:163], v[184:187], v[118:121]
	v_mfma_f32_16x16x32_bf16 v[114:117], v[176:179], v[184:187], v[114:117]
	v_mfma_f32_16x16x32_bf16 v[102:105], v[160:163], v[192:195], v[102:105]
	v_mfma_f32_16x16x32_bf16 v[98:101], v[176:179], v[192:195], v[98:101]
	v_mfma_f32_16x16x32_bf16 v[84:87], v[160:163], v[202:205], v[84:87]
	v_mfma_f32_16x16x32_bf16 v[80:83], v[176:179], v[202:205], v[80:83]
	v_mfma_f32_16x16x32_bf16 v[68:71], v[160:163], v[214:217], v[68:71]
	v_mfma_f32_16x16x32_bf16 v[64:67], v[176:179], v[214:217], v[64:67]
	v_mfma_f32_16x16x32_bf16 v[118:121], v[172:175], v[188:191], v[118:121]
	v_mfma_f32_16x16x32_bf16 v[114:117], v[180:183], v[188:191], v[114:117]
	v_mfma_f32_16x16x32_bf16 v[102:105], v[172:175], v[196:199], v[102:105]
	v_mfma_f32_16x16x32_bf16 v[98:101], v[180:183], v[196:199], v[98:101]
	s_setprio 0
	v_mfma_f32_16x16x32_bf16 v[84:87], v[172:175], v[210:213], v[84:87]
	v_mfma_f32_16x16x32_bf16 v[80:83], v[180:183], v[210:213], v[80:83]
	v_mfma_f32_16x16x32_bf16 v[68:71], v[172:175], v[218:221], v[68:71]
	v_mfma_f32_16x16x32_bf16 v[64:67], v[180:183], v[218:221], v[64:67]
	s_barrier
	s_add_i32 s34, s38, s75
	v_lshl_add_u64 v[164:165], s[84:85], 0, v[96:97]
	s_mov_b32 m0, s34
	ds_read_b128 v[184:187], v171 offset:16384
	ds_read_b128 v[188:191], v171 offset:17408
	ds_read_b128 v[192:195], v171 offset:18432
	ds_read_b128 v[196:199], v171 offset:19456
	ds_read_b128 v[202:205], v171 offset:20480
	ds_read_b128 v[210:213], v171 offset:21504
	ds_read_b128 v[214:217], v171 offset:22528
	ds_read_b128 v[218:221], v171 offset:23552
	global_load_lds_dwordx4 v[164:165], off
	s_add_i32 m0, s34, 0x2000
	s_add_u32 s34, s84, 0x80000
	v_lshl_add_u64 v[222:223], s[84:85], 0, v[142:143]
	s_addc_u32 s35, s85, 0
	s_add_i32 s38, s39, s75
	global_load_lds_dwordx4 v[222:223], off
	v_lshl_add_u64 v[224:225], s[34:35], 0, v[96:97]
	s_mov_b32 m0, s38
	v_lshl_add_u64 v[226:227], s[86:87], 0, v[144:145]
	global_load_lds_dwordx4 v[224:225], off
	v_lshl_add_u64 v[224:225], s[34:35], 0, v[142:143]
	s_add_i32 m0, s38, 0x2000
	s_nop 0
	global_load_lds_dwordx4 v[224:225], off
	v_lshl_add_u64 v[224:225], s[86:87], 0, v[146:147]
	s_mov_b32 m0, s58
	s_nop 0
	global_load_lds_dwordx4 v[224:225], off
	s_mov_b32 m0, s59
	s_nop 0
	global_load_lds_dwordx4 v[226:227], off
	v_cmp_ne_u32_e32 vcc, 0, v243
	s_cbranch_vccnz .Lrx_G_OUT_1
	s_waitcnt vmcnt(8)
.Lrx_G_OUT_1:
	s_waitcnt vmcnt(44)
	v_mov_b32_e32 v243, 0
	s_waitcnt lgkmcnt(0)
	s_setprio 1
	s_barrier
	v_mfma_f32_16x16x32_bf16 v[60:63], v[130:133], v[184:187], v[60:63]
	v_mfma_f32_16x16x32_bf16 v[56:59], v[152:155], v[184:187], v[56:59]
	v_mfma_f32_16x16x32_bf16 v[44:47], v[130:133], v[192:195], v[44:47]
	v_mfma_f32_16x16x32_bf16 v[40:43], v[152:155], v[192:195], v[40:43]
	v_mfma_f32_16x16x32_bf16 v[28:31], v[130:133], v[202:205], v[28:31]
	v_mfma_f32_16x16x32_bf16 v[24:27], v[152:155], v[202:205], v[24:27]
	v_mfma_f32_16x16x32_bf16 v[12:15], v[130:133], v[214:217], v[12:15]
	v_mfma_f32_16x16x32_bf16 v[8:11], v[152:155], v[214:217], v[8:11]
	v_mfma_f32_16x16x32_bf16 v[60:63], v[134:137], v[188:191], v[60:63]
	v_mfma_f32_16x16x32_bf16 v[56:59], v[156:159], v[188:191], v[56:59]
	v_mfma_f32_16x16x32_bf16 v[44:47], v[134:137], v[196:199], v[44:47]
	v_mfma_f32_16x16x32_bf16 v[40:43], v[156:159], v[196:199], v[40:43]
	v_mfma_f32_16x16x32_bf16 v[28:31], v[134:137], v[210:213], v[28:31]
	v_mfma_f32_16x16x32_bf16 v[24:27], v[156:159], v[210:213], v[24:27]
	v_mfma_f32_16x16x32_bf16 v[12:15], v[134:137], v[218:221], v[12:15]
	v_mfma_f32_16x16x32_bf16 v[8:11], v[156:159], v[218:221], v[8:11]
	v_mfma_f32_16x16x32_bf16 v[52:55], v[160:163], v[184:187], v[52:55]
	v_mfma_f32_16x16x32_bf16 v[48:51], v[176:179], v[184:187], v[48:51]
	v_mfma_f32_16x16x32_bf16 v[36:39], v[160:163], v[192:195], v[36:39]
	v_mfma_f32_16x16x32_bf16 v[32:35], v[176:179], v[192:195], v[32:35]
	v_mfma_f32_16x16x32_bf16 v[20:23], v[160:163], v[202:205], v[20:23]
	v_mfma_f32_16x16x32_bf16 v[16:19], v[176:179], v[202:205], v[16:19]
	v_mfma_f32_16x16x32_bf16 v[4:7], v[160:163], v[214:217], v[4:7]
	v_mfma_f32_16x16x32_bf16 v[0:3], v[176:179], v[214:217], v[0:3]
	v_mfma_f32_16x16x32_bf16 v[52:55], v[172:175], v[188:191], v[52:55]
	v_mfma_f32_16x16x32_bf16 v[48:51], v[180:183], v[188:191], v[48:51]
	v_mfma_f32_16x16x32_bf16 v[36:39], v[172:175], v[196:199], v[36:39]
	v_mfma_f32_16x16x32_bf16 v[32:35], v[180:183], v[196:199], v[32:35]
	s_setprio 0
	v_mfma_f32_16x16x32_bf16 v[20:23], v[172:175], v[210:213], v[20:23]
	v_mfma_f32_16x16x32_bf16 v[16:19], v[180:183], v[210:213], v[16:19]
	v_mfma_f32_16x16x32_bf16 v[4:7], v[172:175], v[218:221], v[4:7]
	v_mfma_f32_16x16x32_bf16 v[0:3], v[180:183], v[218:221], v[0:3]
	s_barrier
	s_add_i32 s38, 0, 0x18000
	s_add_i32 s39, 0, 0x1c000
	v_add_u32_e32 v156, s38, v169
	v_add_u32_e32 v180, s39, v169
	ds_read_b128 v[130:133], v156
	ds_read_b128 v[134:137], v156 offset:1024
	ds_read_b128 v[152:155], v156 offset:2048
	ds_read_b128 v[156:159], v156 offset:3072
	ds_read_b128 v[160:163], v180
	ds_read_b128 v[172:175], v180 offset:1024
	ds_read_b128 v[176:179], v180 offset:2048
	ds_read_b128 v[180:183], v180 offset:3072
	s_add_u32 s34, s86, 0x80000
	s_addc_u32 s35, s87, 0
	s_mov_b32 m0, s79
	v_lshl_add_u64 v[228:229], s[34:35], 0, v[146:147]
	ds_read_b128 v[184:187], v171 offset:32768
	ds_read_b128 v[188:191], v171 offset:33792
	ds_read_b128 v[192:195], v171 offset:34816
	ds_read_b128 v[196:199], v171 offset:35840
	ds_read_b128 v[202:205], v171 offset:36864
	ds_read_b128 v[210:213], v171 offset:37888
	ds_read_b128 v[214:217], v171 offset:38912
	ds_read_b128 v[218:221], v171 offset:39936
	global_load_lds_dwordx4 v[228:229], off
	v_lshl_add_u64 v[228:229], s[34:35], 0, v[144:145]
	s_mov_b32 m0, s90
	s_nop 0
	global_load_lds_dwordx4 v[228:229], off
	s_waitcnt vmcnt(8)
	s_waitcnt lgkmcnt(0)
	s_setprio 1
	s_barrier
	v_mfma_f32_16x16x32_bf16 v[126:129], v[130:133], v[184:187], v[126:129]
	v_mfma_f32_16x16x32_bf16 v[122:125], v[152:155], v[184:187], v[122:125]
	v_mfma_f32_16x16x32_bf16 v[110:113], v[130:133], v[192:195], v[110:113]
	v_mfma_f32_16x16x32_bf16 v[106:109], v[152:155], v[192:195], v[106:109]
	v_mfma_f32_16x16x32_bf16 v[92:95], v[130:133], v[202:205], v[92:95]
	v_mfma_f32_16x16x32_bf16 v[88:91], v[152:155], v[202:205], v[88:91]
	v_mfma_f32_16x16x32_bf16 v[76:79], v[130:133], v[214:217], v[76:79]
	v_mfma_f32_16x16x32_bf16 v[72:75], v[152:155], v[214:217], v[72:75]
	v_mfma_f32_16x16x32_bf16 v[126:129], v[134:137], v[188:191], v[126:129]
	v_mfma_f32_16x16x32_bf16 v[122:125], v[156:159], v[188:191], v[122:125]
	v_mfma_f32_16x16x32_bf16 v[110:113], v[134:137], v[196:199], v[110:113]
	v_mfma_f32_16x16x32_bf16 v[106:109], v[156:159], v[196:199], v[106:109]
	v_mfma_f32_16x16x32_bf16 v[92:95], v[134:137], v[210:213], v[92:95]
	v_mfma_f32_16x16x32_bf16 v[88:91], v[156:159], v[210:213], v[88:91]
	v_mfma_f32_16x16x32_bf16 v[76:79], v[134:137], v[218:221], v[76:79]
	v_mfma_f32_16x16x32_bf16 v[72:75], v[156:159], v[218:221], v[72:75]
	v_mfma_f32_16x16x32_bf16 v[118:121], v[160:163], v[184:187], v[118:121]
	v_mfma_f32_16x16x32_bf16 v[114:117], v[176:179], v[184:187], v[114:117]
	v_mfma_f32_16x16x32_bf16 v[102:105], v[160:163], v[192:195], v[102:105]
	v_mfma_f32_16x16x32_bf16 v[98:101], v[176:179], v[192:195], v[98:101]
	v_mfma_f32_16x16x32_bf16 v[84:87], v[160:163], v[202:205], v[84:87]
	v_mfma_f32_16x16x32_bf16 v[80:83], v[176:179], v[202:205], v[80:83]
	v_mfma_f32_16x16x32_bf16 v[68:71], v[160:163], v[214:217], v[68:71]
	v_mfma_f32_16x16x32_bf16 v[64:67], v[176:179], v[214:217], v[64:67]
	v_mfma_f32_16x16x32_bf16 v[118:121], v[172:175], v[188:191], v[118:121]
	v_mfma_f32_16x16x32_bf16 v[114:117], v[180:183], v[188:191], v[114:117]
	v_mfma_f32_16x16x32_bf16 v[102:105], v[172:175], v[196:199], v[102:105]
	v_mfma_f32_16x16x32_bf16 v[98:101], v[180:183], v[196:199], v[98:101]
	s_setprio 0
	v_mfma_f32_16x16x32_bf16 v[84:87], v[172:175], v[210:213], v[84:87]
	v_mfma_f32_16x16x32_bf16 v[80:83], v[180:183], v[210:213], v[80:83]
	v_mfma_f32_16x16x32_bf16 v[68:71], v[172:175], v[218:221], v[68:71]
	v_mfma_f32_16x16x32_bf16 v[64:67], v[180:183], v[218:221], v[64:67]
	s_barrier
	s_add_i32 s34, s38, s75
	v_lshl_add_u64 v[164:165], v[164:165], 0, s[64:65]
	s_mov_b32 m0, s34
	ds_read_b128 v[184:187], v171 offset:49152
	ds_read_b128 v[188:191], v171 offset:50176
	ds_read_b128 v[192:195], v171 offset:51200
	ds_read_b128 v[196:199], v171 offset:52224
	ds_read_b128 v[202:205], v171 offset:53248
	ds_read_b128 v[210:213], v171 offset:54272
	ds_read_b128 v[214:217], v171 offset:55296
	ds_read_b128 v[218:221], v171 offset:56320
	global_load_lds_dwordx4 v[164:165], off
	s_add_i32 m0, s34, 0x2000
	s_add_u32 s34, s84, 0x80080
	v_lshl_add_u64 v[164:165], v[222:223], 0, s[64:65]
	s_addc_u32 s35, s85, 0
	s_add_i32 s38, s39, s75
	global_load_lds_dwordx4 v[164:165], off
	v_lshl_add_u64 v[164:165], s[34:35], 0, v[96:97]
	s_mov_b32 m0, s38
	s_nop 0
	global_load_lds_dwordx4 v[164:165], off
	v_lshl_add_u64 v[164:165], s[34:35], 0, v[142:143]
	s_add_i32 m0, s38, 0x2000
	s_nop 0
	global_load_lds_dwordx4 v[164:165], off
	v_lshl_add_u64 v[164:165], v[224:225], 0, s[64:65]
	s_mov_b32 m0, s94
	s_nop 0
	global_load_lds_dwordx4 v[164:165], off
	v_lshl_add_u64 v[164:165], v[226:227], 0, s[64:65]
	s_mov_b32 m0, s95
	s_nop 0
	global_load_lds_dwordx4 v[164:165], off
	s_waitcnt vmcnt(8)
	s_waitcnt lgkmcnt(0)
	s_setprio 1
	s_barrier
	v_mfma_f32_16x16x32_bf16 v[60:63], v[130:133], v[184:187], v[60:63]
	v_mfma_f32_16x16x32_bf16 v[56:59], v[152:155], v[184:187], v[56:59]
	v_mfma_f32_16x16x32_bf16 v[44:47], v[130:133], v[192:195], v[44:47]
	v_mfma_f32_16x16x32_bf16 v[40:43], v[152:155], v[192:195], v[40:43]
	v_mfma_f32_16x16x32_bf16 v[28:31], v[130:133], v[202:205], v[28:31]
	v_mfma_f32_16x16x32_bf16 v[24:27], v[152:155], v[202:205], v[24:27]
	v_mfma_f32_16x16x32_bf16 v[12:15], v[130:133], v[214:217], v[12:15]
	v_mfma_f32_16x16x32_bf16 v[8:11], v[152:155], v[214:217], v[8:11]
	v_mfma_f32_16x16x32_bf16 v[60:63], v[134:137], v[188:191], v[60:63]
	v_mfma_f32_16x16x32_bf16 v[56:59], v[156:159], v[188:191], v[56:59]
	v_mfma_f32_16x16x32_bf16 v[44:47], v[134:137], v[196:199], v[44:47]
	v_mfma_f32_16x16x32_bf16 v[40:43], v[156:159], v[196:199], v[40:43]
	v_mfma_f32_16x16x32_bf16 v[28:31], v[134:137], v[210:213], v[28:31]
	v_mfma_f32_16x16x32_bf16 v[24:27], v[156:159], v[210:213], v[24:27]
	v_mfma_f32_16x16x32_bf16 v[12:15], v[134:137], v[218:221], v[12:15]
	v_mfma_f32_16x16x32_bf16 v[8:11], v[156:159], v[218:221], v[8:11]
	v_mfma_f32_16x16x32_bf16 v[52:55], v[160:163], v[184:187], v[52:55]
	v_mfma_f32_16x16x32_bf16 v[48:51], v[176:179], v[184:187], v[48:51]
	v_mfma_f32_16x16x32_bf16 v[36:39], v[160:163], v[192:195], v[36:39]
	v_mfma_f32_16x16x32_bf16 v[32:35], v[176:179], v[192:195], v[32:35]
	v_mfma_f32_16x16x32_bf16 v[20:23], v[160:163], v[202:205], v[20:23]
	v_mfma_f32_16x16x32_bf16 v[16:19], v[176:179], v[202:205], v[16:19]
	v_mfma_f32_16x16x32_bf16 v[4:7], v[160:163], v[214:217], v[4:7]
	v_mfma_f32_16x16x32_bf16 v[0:3], v[176:179], v[214:217], v[0:3]
	v_mfma_f32_16x16x32_bf16 v[52:55], v[172:175], v[188:191], v[52:55]
	v_mfma_f32_16x16x32_bf16 v[48:51], v[180:183], v[188:191], v[48:51]
	v_mfma_f32_16x16x32_bf16 v[36:39], v[172:175], v[196:199], v[36:39]
	v_mfma_f32_16x16x32_bf16 v[32:35], v[180:183], v[196:199], v[32:35]
	s_setprio 0
	v_mfma_f32_16x16x32_bf16 v[20:23], v[172:175], v[210:213], v[20:23]
	v_mfma_f32_16x16x32_bf16 v[16:19], v[180:183], v[210:213], v[16:19]
	v_mfma_f32_16x16x32_bf16 v[4:7], v[172:175], v[218:221], v[4:7]
	v_mfma_f32_16x16x32_bf16 v[0:3], v[180:183], v[218:221], v[0:3]
	s_barrier
	s_add_i32 s33, s33, 2
	s_add_u32 s44, s44, 0x100
	s_addc_u32 s45, s45, 0
	s_add_u32 s28, s28, 0x100
	s_addc_u32 s31, s31, 0
	s_cmp_gt_u32 s33, 29
	s_cbranch_scc0 .LBB0_1038
	v_mov_b32_e32 v243, 1
	v_readlane_b32 s0, v251, 54
	v_readlane_b32 s1, v251, 55
	s_and_b64 vcc, exec, s[0:1]
	s_cbranch_vccz .LBB0_1041
	s_barrier

.Lrx_G_DN_0:
	s_waitcnt vmcnt(44)
	s_waitcnt lgkmcnt(0)
	s_setprio 1
	s_barrier
	v_mfma_f32_16x16x32_bf16 v[126:129], v[144:147], v[184:187], v[126:129]
	v_mfma_f32_16x16x32_bf16 v[122:125], v[160:163], v[184:187], v[122:125]
	v_mfma_f32_16x16x32_bf16 v[110:113], v[144:147], v[192:195], v[110:113]
	v_mfma_f32_16x16x32_bf16 v[106:109], v[160:163], v[192:195], v[106:109]
	v_mfma_f32_16x16x32_bf16 v[92:95], v[144:147], v[202:205], v[92:95]
	v_mfma_f32_16x16x32_bf16 v[88:91], v[160:163], v[202:205], v[88:91]
	v_mfma_f32_16x16x32_bf16 v[76:79], v[144:147], v[214:217], v[76:79]
	v_mfma_f32_16x16x32_bf16 v[72:75], v[160:163], v[214:217], v[72:75]
	v_mfma_f32_16x16x32_bf16 v[126:129], v[154:157], v[188:191], v[126:129]
	v_mfma_f32_16x16x32_bf16 v[122:125], v[164:167], v[188:191], v[122:125]
	v_mfma_f32_16x16x32_bf16 v[110:113], v[154:157], v[196:199], v[110:113]
	v_mfma_f32_16x16x32_bf16 v[106:109], v[164:167], v[196:199], v[106:109]
	v_mfma_f32_16x16x32_bf16 v[92:95], v[154:157], v[210:213], v[92:95]
	v_mfma_f32_16x16x32_bf16 v[88:91], v[164:167], v[210:213], v[88:91]
	v_mfma_f32_16x16x32_bf16 v[76:79], v[154:157], v[218:221], v[76:79]
	v_mfma_f32_16x16x32_bf16 v[72:75], v[164:167], v[218:221], v[72:75]
	v_mfma_f32_16x16x32_bf16 v[118:121], v[168:171], v[184:187], v[118:121]
	v_mfma_f32_16x16x32_bf16 v[114:117], v[176:179], v[184:187], v[114:117]
	v_mfma_f32_16x16x32_bf16 v[102:105], v[168:171], v[192:195], v[102:105]
	v_mfma_f32_16x16x32_bf16 v[98:101], v[176:179], v[192:195], v[98:101]
	v_mfma_f32_16x16x32_bf16 v[84:87], v[168:171], v[202:205], v[84:87]
	v_mfma_f32_16x16x32_bf16 v[80:83], v[176:179], v[202:205], v[80:83]
	v_mfma_f32_16x16x32_bf16 v[68:71], v[168:171], v[214:217], v[68:71]
	v_mfma_f32_16x16x32_bf16 v[64:67], v[176:179], v[214:217], v[64:67]
	v_mfma_f32_16x16x32_bf16 v[118:121], v[172:175], v[188:191], v[118:121]
	v_mfma_f32_16x16x32_bf16 v[114:117], v[180:183], v[188:191], v[114:117]
	v_mfma_f32_16x16x32_bf16 v[102:105], v[172:175], v[196:199], v[102:105]
	v_mfma_f32_16x16x32_bf16 v[98:101], v[180:183], v[196:199], v[98:101]
	s_setprio 0
	v_mfma_f32_16x16x32_bf16 v[84:87], v[172:175], v[210:213], v[84:87]
	v_mfma_f32_16x16x32_bf16 v[80:83], v[180:183], v[210:213], v[80:83]
	v_mfma_f32_16x16x32_bf16 v[68:71], v[172:175], v[218:221], v[68:71]
	v_mfma_f32_16x16x32_bf16 v[64:67], v[180:183], v[218:221], v[64:67]
	s_barrier
	s_add_i32 s54, s54, s75
	v_lshl_add_u64 v[148:149], s[44:45], 0, v[96:97]
	s_mov_b32 m0, s54
	ds_read_b128 v[184:187], v159 offset:16384
	ds_read_b128 v[188:191], v159 offset:17408
	ds_read_b128 v[192:195], v159 offset:18432
	ds_read_b128 v[196:199], v159 offset:19456
	ds_read_b128 v[202:205], v159 offset:20480
	ds_read_b128 v[210:213], v159 offset:21504
	ds_read_b128 v[214:217], v159 offset:22528
	ds_read_b128 v[218:221], v159 offset:23552
	global_load_lds_dwordx4 v[148:149], off
	s_add_i32 m0, s54, 0x2000
	s_add_u32 s54, s44, 0x200000
	v_lshl_add_u64 v[222:223], s[44:45], 0, v[134:135]
	s_addc_u32 s55, s45, 0
	s_add_i32 s35, s35, s75
	global_load_lds_dwordx4 v[222:223], off
	v_lshl_add_u64 v[224:225], s[54:55], 0, v[96:97]
	s_mov_b32 m0, s35
	v_lshl_add_u64 v[226:227], s[52:53], 0, v[136:137]
	global_load_lds_dwordx4 v[224:225], off
	v_lshl_add_u64 v[224:225], s[54:55], 0, v[134:135]
	s_add_i32 m0, s35, 0x2000
	s_nop 0
	global_load_lds_dwordx4 v[224:225], off
	v_lshl_add_u64 v[224:225], s[52:53], 0, v[138:139]
	s_mov_b32 m0, s59
	s_nop 0
	global_load_lds_dwordx4 v[224:225], off
	s_mov_b32 m0, s68
	s_nop 0
	global_load_lds_dwordx4 v[226:227], off
	v_cmp_ne_u32_e32 vcc, 0, v243
	s_cbranch_vccnz .Lrx_G_DN_1
	s_waitcnt vmcnt(8)
.Lrx_G_DN_1:
	s_waitcnt vmcnt(44)
	v_mov_b32_e32 v243, 0
	s_waitcnt lgkmcnt(0)
	s_setprio 1
	s_barrier
	v_mfma_f32_16x16x32_bf16 v[60:63], v[144:147], v[184:187], v[60:63]
	v_mfma_f32_16x16x32_bf16 v[56:59], v[160:163], v[184:187], v[56:59]
	v_mfma_f32_16x16x32_bf16 v[44:47], v[144:147], v[192:195], v[44:47]
	v_mfma_f32_16x16x32_bf16 v[40:43], v[160:163], v[192:195], v[40:43]
	v_mfma_f32_16x16x32_bf16 v[28:31], v[144:147], v[202:205], v[28:31]
	v_mfma_f32_16x16x32_bf16 v[24:27], v[160:163], v[202:205], v[24:27]
	v_mfma_f32_16x16x32_bf16 v[12:15], v[144:147], v[214:217], v[12:15]
	v_mfma_f32_16x16x32_bf16 v[8:11], v[160:163], v[214:217], v[8:11]
	v_mfma_f32_16x16x32_bf16 v[60:63], v[154:157], v[188:191], v[60:63]
	v_mfma_f32_16x16x32_bf16 v[56:59], v[164:167], v[188:191], v[56:59]
	v_mfma_f32_16x16x32_bf16 v[44:47], v[154:157], v[196:199], v[44:47]
	v_mfma_f32_16x16x32_bf16 v[40:43], v[164:167], v[196:199], v[40:43]
	v_mfma_f32_16x16x32_bf16 v[28:31], v[154:157], v[210:213], v[28:31]
	v_mfma_f32_16x16x32_bf16 v[24:27], v[164:167], v[210:213], v[24:27]
	v_mfma_f32_16x16x32_bf16 v[12:15], v[154:157], v[218:221], v[12:15]
	v_mfma_f32_16x16x32_bf16 v[8:11], v[164:167], v[218:221], v[8:11]
	v_mfma_f32_16x16x32_bf16 v[52:55], v[168:171], v[184:187], v[52:55]
	v_mfma_f32_16x16x32_bf16 v[48:51], v[176:179], v[184:187], v[48:51]
	v_mfma_f32_16x16x32_bf16 v[36:39], v[168:171], v[192:195], v[36:39]
	v_mfma_f32_16x16x32_bf16 v[32:35], v[176:179], v[192:195], v[32:35]
	v_mfma_f32_16x16x32_bf16 v[20:23], v[168:171], v[202:205], v[20:23]
	v_mfma_f32_16x16x32_bf16 v[16:19], v[176:179], v[202:205], v[16:19]
	v_mfma_f32_16x16x32_bf16 v[4:7], v[168:171], v[214:217], v[4:7]
	v_mfma_f32_16x16x32_bf16 v[0:3], v[176:179], v[214:217], v[0:3]
	v_mfma_f32_16x16x32_bf16 v[52:55], v[172:175], v[188:191], v[52:55]
	v_mfma_f32_16x16x32_bf16 v[48:51], v[180:183], v[188:191], v[48:51]
	v_mfma_f32_16x16x32_bf16 v[36:39], v[172:175], v[196:199], v[36:39]
	v_mfma_f32_16x16x32_bf16 v[32:35], v[180:183], v[196:199], v[32:35]
	s_setprio 0
	v_mfma_f32_16x16x32_bf16 v[20:23], v[172:175], v[210:213], v[20:23]
	v_mfma_f32_16x16x32_bf16 v[16:19], v[180:183], v[210:213], v[16:19]
	v_mfma_f32_16x16x32_bf16 v[4:7], v[172:175], v[218:221], v[4:7]
	v_mfma_f32_16x16x32_bf16 v[0:3], v[180:183], v[218:221], v[0:3]
	s_barrier
	s_add_i32 s35, 0, 0x18000
	s_add_i32 s54, 0, 0x1c000
	v_add_u32_e32 v164, s35, v153
	v_add_u32_e32 v180, s54, v153
	ds_read_b128 v[144:147], v164
	ds_read_b128 v[154:157], v164 offset:1024
	ds_read_b128 v[160:163], v164 offset:2048
	ds_read_b128 v[164:167], v164 offset:3072
	ds_read_b128 v[168:171], v180
	ds_read_b128 v[172:175], v180 offset:1024
	ds_read_b128 v[176:179], v180 offset:2048
	ds_read_b128 v[180:183], v180 offset:3072
	s_add_u32 s52, s52, 0x200000
	s_addc_u32 s53, s53, 0
	s_mov_b32 m0, s69
	v_lshl_add_u64 v[228:229], s[52:53], 0, v[138:139]
	ds_read_b128 v[184:187], v159 offset:32768
	ds_read_b128 v[188:191], v159 offset:33792
	ds_read_b128 v[192:195], v159 offset:34816
	ds_read_b128 v[196:199], v159 offset:35840
	ds_read_b128 v[202:205], v159 offset:36864
	ds_read_b128 v[210:213], v159 offset:37888
	ds_read_b128 v[214:217], v159 offset:38912
	ds_read_b128 v[218:221], v159 offset:39936
	global_load_lds_dwordx4 v[228:229], off
	v_lshl_add_u64 v[228:229], s[52:53], 0, v[136:137]
	s_mov_b32 m0, s79
	s_nop 0
	global_load_lds_dwordx4 v[228:229], off
	s_waitcnt vmcnt(8)
	s_waitcnt lgkmcnt(0)
	s_setprio 1
	s_barrier
	v_mfma_f32_16x16x32_bf16 v[126:129], v[144:147], v[184:187], v[126:129]
	v_mfma_f32_16x16x32_bf16 v[122:125], v[160:163], v[184:187], v[122:125]
	v_mfma_f32_16x16x32_bf16 v[110:113], v[144:147], v[192:195], v[110:113]
	v_mfma_f32_16x16x32_bf16 v[106:109], v[160:163], v[192:195], v[106:109]
	v_mfma_f32_16x16x32_bf16 v[92:95], v[144:147], v[202:205], v[92:95]
	v_mfma_f32_16x16x32_bf16 v[88:91], v[160:163], v[202:205], v[88:91]
	v_mfma_f32_16x16x32_bf16 v[76:79], v[144:147], v[214:217], v[76:79]
	v_mfma_f32_16x16x32_bf16 v[72:75], v[160:163], v[214:217], v[72:75]
	v_mfma_f32_16x16x32_bf16 v[126:129], v[154:157], v[188:191], v[126:129]
	v_mfma_f32_16x16x32_bf16 v[122:125], v[164:167], v[188:191], v[122:125]
	v_mfma_f32_16x16x32_bf16 v[110:113], v[154:157], v[196:199], v[110:113]
	v_mfma_f32_16x16x32_bf16 v[106:109], v[164:167], v[196:199], v[106:109]
	v_mfma_f32_16x16x32_bf16 v[92:95], v[154:157], v[210:213], v[92:95]
	v_mfma_f32_16x16x32_bf16 v[88:91], v[164:167], v[210:213], v[88:91]
	v_mfma_f32_16x16x32_bf16 v[76:79], v[154:157], v[218:221], v[76:79]
	v_mfma_f32_16x16x32_bf16 v[72:75], v[164:167], v[218:221], v[72:75]
	v_mfma_f32_16x16x32_bf16 v[118:121], v[168:171], v[184:187], v[118:121]
	v_mfma_f32_16x16x32_bf16 v[114:117], v[176:179], v[184:187], v[114:117]
	v_mfma_f32_16x16x32_bf16 v[102:105], v[168:171], v[192:195], v[102:105]
	v_mfma_f32_16x16x32_bf16 v[98:101], v[176:179], v[192:195], v[98:101]
	v_mfma_f32_16x16x32_bf16 v[84:87], v[168:171], v[202:205], v[84:87]
	v_mfma_f32_16x16x32_bf16 v[80:83], v[176:179], v[202:205], v[80:83]
	v_mfma_f32_16x16x32_bf16 v[68:71], v[168:171], v[214:217], v[68:71]
	v_mfma_f32_16x16x32_bf16 v[64:67], v[176:179], v[214:217], v[64:67]
	v_mfma_f32_16x16x32_bf16 v[118:121], v[172:175], v[188:191], v[118:121]
	v_mfma_f32_16x16x32_bf16 v[114:117], v[180:183], v[188:191], v[114:117]
	v_mfma_f32_16x16x32_bf16 v[102:105], v[172:175], v[196:199], v[102:105]
	v_mfma_f32_16x16x32_bf16 v[98:101], v[180:183], v[196:199], v[98:101]
	s_setprio 0
	v_mfma_f32_16x16x32_bf16 v[84:87], v[172:175], v[210:213], v[84:87]
	v_mfma_f32_16x16x32_bf16 v[80:83], v[180:183], v[210:213], v[80:83]
	v_mfma_f32_16x16x32_bf16 v[68:71], v[172:175], v[218:221], v[68:71]
	v_mfma_f32_16x16x32_bf16 v[64:67], v[180:183], v[218:221], v[64:67]
	s_barrier
	s_add_i32 s35, s35, s75
	v_lshl_add_u64 v[148:149], v[148:149], 0, s[64:65]
	s_mov_b32 m0, s35
	ds_read_b128 v[184:187], v159 offset:49152
	ds_read_b128 v[188:191], v159 offset:50176
	ds_read_b128 v[192:195], v159 offset:51200
	ds_read_b128 v[196:199], v159 offset:52224
	ds_read_b128 v[202:205], v159 offset:53248
	ds_read_b128 v[210:213], v159 offset:54272
	ds_read_b128 v[214:217], v159 offset:55296
	ds_read_b128 v[218:221], v159 offset:56320
	global_load_lds_dwordx4 v[148:149], off
	s_add_i32 m0, s35, 0x2000
	s_add_u32 s44, s44, 0x200080
	v_lshl_add_u64 v[148:149], v[222:223], 0, s[64:65]
	s_addc_u32 s45, s45, 0
	s_add_i32 s35, s54, s75
	global_load_lds_dwordx4 v[148:149], off
	v_lshl_add_u64 v[148:149], s[44:45], 0, v[96:97]
	s_mov_b32 m0, s35
	s_nop 0
	global_load_lds_dwordx4 v[148:149], off
	v_lshl_add_u64 v[148:149], s[44:45], 0, v[134:135]
	s_add_i32 m0, s35, 0x2000
	s_nop 0
	global_load_lds_dwordx4 v[148:149], off
	v_lshl_add_u64 v[148:149], v[224:225], 0, s[64:65]
	s_mov_b32 m0, s10
	s_nop 0
	global_load_lds_dwordx4 v[148:149], off
	v_lshl_add_u64 v[148:149], v[226:227], 0, s[64:65]
	s_mov_b32 m0, s77
	s_nop 0
	global_load_lds_dwordx4 v[148:149], off
	s_waitcnt vmcnt(8)
	s_waitcnt lgkmcnt(0)
	s_setprio 1
	s_barrier
	v_mfma_f32_16x16x32_bf16 v[60:63], v[144:147], v[184:187], v[60:63]
	v_mfma_f32_16x16x32_bf16 v[56:59], v[160:163], v[184:187], v[56:59]
	v_mfma_f32_16x16x32_bf16 v[44:47], v[144:147], v[192:195], v[44:47]
	v_mfma_f32_16x16x32_bf16 v[40:43], v[160:163], v[192:195], v[40:43]
	v_mfma_f32_16x16x32_bf16 v[28:31], v[144:147], v[202:205], v[28:31]
	v_mfma_f32_16x16x32_bf16 v[24:27], v[160:163], v[202:205], v[24:27]
	v_mfma_f32_16x16x32_bf16 v[12:15], v[144:147], v[214:217], v[12:15]
	v_mfma_f32_16x16x32_bf16 v[8:11], v[160:163], v[214:217], v[8:11]
	v_mfma_f32_16x16x32_bf16 v[60:63], v[154:157], v[188:191], v[60:63]
	v_mfma_f32_16x16x32_bf16 v[56:59], v[164:167], v[188:191], v[56:59]
	v_mfma_f32_16x16x32_bf16 v[44:47], v[154:157], v[196:199], v[44:47]
	v_mfma_f32_16x16x32_bf16 v[40:43], v[164:167], v[196:199], v[40:43]
	v_mfma_f32_16x16x32_bf16 v[28:31], v[154:157], v[210:213], v[28:31]
	v_mfma_f32_16x16x32_bf16 v[24:27], v[164:167], v[210:213], v[24:27]
	v_mfma_f32_16x16x32_bf16 v[12:15], v[154:157], v[218:221], v[12:15]
	v_mfma_f32_16x16x32_bf16 v[8:11], v[164:167], v[218:221], v[8:11]
	v_mfma_f32_16x16x32_bf16 v[52:55], v[168:171], v[184:187], v[52:55]
	v_mfma_f32_16x16x32_bf16 v[48:51], v[176:179], v[184:187], v[48:51]
	v_mfma_f32_16x16x32_bf16 v[36:39], v[168:171], v[192:195], v[36:39]
	v_mfma_f32_16x16x32_bf16 v[32:35], v[176:179], v[192:195], v[32:35]
	v_mfma_f32_16x16x32_bf16 v[20:23], v[168:171], v[202:205], v[20:23]
	v_mfma_f32_16x16x32_bf16 v[16:19], v[176:179], v[202:205], v[16:19]
	v_mfma_f32_16x16x32_bf16 v[4:7], v[168:171], v[214:217], v[4:7]
	v_mfma_f32_16x16x32_bf16 v[0:3], v[176:179], v[214:217], v[0:3]
	v_mfma_f32_16x16x32_bf16 v[52:55], v[172:175], v[188:191], v[52:55]
	v_mfma_f32_16x16x32_bf16 v[48:51], v[180:183], v[188:191], v[48:51]
	v_mfma_f32_16x16x32_bf16 v[36:39], v[172:175], v[196:199], v[36:39]
	v_mfma_f32_16x16x32_bf16 v[32:35], v[180:183], v[196:199], v[32:35]
	s_setprio 0
	v_mfma_f32_16x16x32_bf16 v[20:23], v[172:175], v[210:213], v[20:23]
	v_mfma_f32_16x16x32_bf16 v[16:19], v[180:183], v[210:213], v[16:19]
	v_mfma_f32_16x16x32_bf16 v[4:7], v[172:175], v[218:221], v[4:7]
	v_mfma_f32_16x16x32_bf16 v[0:3], v[180:183], v[218:221], v[0:3]
	s_barrier
	s_add_i32 s33, s33, 2
	s_add_u32 s42, s42, 0x100
	s_addc_u32 s43, s43, 0
	s_add_u32 s20, s20, 0x100
	s_addc_u32 s28, s28, 0
	s_cmpk_gt_u32 s33, 0x7d
	s_cbranch_scc0 .LBB0_1265
	v_mov_b32_e32 v243, 1
	v_readlane_b32 s6, v251, 54
	v_readlane_b32 s7, v251, 55
	s_and_b64 vcc, exec, s[6:7]
	s_movk_i32 s53, 0x6000
	s_cbranch_vccz .LBB0_1268
	s_barrier

.Lrx_G_UP_0:
	s_waitcnt vmcnt(24)
	s_waitcnt lgkmcnt(0)
	s_setprio 1
	s_barrier
	v_mfma_f32_16x16x32_bf16 v[126:129], v[154:157], v[186:189], v[126:129]
	v_mfma_f32_16x16x32_bf16 v[122:125], v[162:165], v[186:189], v[122:125]
	v_mfma_f32_16x16x32_bf16 v[110:113], v[154:157], v[194:197], v[110:113]
	v_mfma_f32_16x16x32_bf16 v[106:109], v[162:165], v[194:197], v[106:109]
	v_mfma_f32_16x16x32_bf16 v[92:95], v[154:157], v[210:213], v[92:95]
	v_mfma_f32_16x16x32_bf16 v[88:91], v[162:165], v[210:213], v[88:91]
	v_mfma_f32_16x16x32_bf16 v[76:79], v[154:157], v[218:221], v[76:79]
	v_mfma_f32_16x16x32_bf16 v[72:75], v[162:165], v[218:221], v[72:75]
	v_mfma_f32_16x16x32_bf16 v[126:129], v[158:161], v[190:193], v[126:129]
	v_mfma_f32_16x16x32_bf16 v[122:125], v[166:169], v[190:193], v[122:125]
	v_mfma_f32_16x16x32_bf16 v[110:113], v[158:161], v[202:205], v[110:113]
	v_mfma_f32_16x16x32_bf16 v[106:109], v[166:169], v[202:205], v[106:109]
	v_mfma_f32_16x16x32_bf16 v[92:95], v[158:161], v[214:217], v[92:95]
	v_mfma_f32_16x16x32_bf16 v[88:91], v[166:169], v[214:217], v[88:91]
	v_mfma_f32_16x16x32_bf16 v[76:79], v[158:161], v[222:225], v[76:79]
	v_mfma_f32_16x16x32_bf16 v[72:75], v[166:169], v[222:225], v[72:75]
	v_mfma_f32_16x16x32_bf16 v[118:121], v[170:173], v[186:189], v[118:121]
	v_mfma_f32_16x16x32_bf16 v[114:117], v[178:181], v[186:189], v[114:117]
	v_mfma_f32_16x16x32_bf16 v[102:105], v[170:173], v[194:197], v[102:105]
	v_mfma_f32_16x16x32_bf16 v[98:101], v[178:181], v[194:197], v[98:101]
	v_mfma_f32_16x16x32_bf16 v[84:87], v[170:173], v[210:213], v[84:87]
	v_mfma_f32_16x16x32_bf16 v[80:83], v[178:181], v[210:213], v[80:83]
	v_mfma_f32_16x16x32_bf16 v[68:71], v[170:173], v[218:221], v[68:71]
	v_mfma_f32_16x16x32_bf16 v[64:67], v[178:181], v[218:221], v[64:67]
	v_mfma_f32_16x16x32_bf16 v[118:121], v[174:177], v[190:193], v[118:121]
	v_mfma_f32_16x16x32_bf16 v[114:117], v[182:185], v[190:193], v[114:117]
	v_mfma_f32_16x16x32_bf16 v[102:105], v[174:177], v[202:205], v[102:105]
	v_mfma_f32_16x16x32_bf16 v[98:101], v[182:185], v[202:205], v[98:101]
	s_setprio 0
	v_mfma_f32_16x16x32_bf16 v[84:87], v[174:177], v[214:217], v[84:87]
	v_mfma_f32_16x16x32_bf16 v[80:83], v[182:185], v[214:217], v[80:83]
	v_mfma_f32_16x16x32_bf16 v[68:71], v[174:177], v[222:225], v[68:71]
	v_mfma_f32_16x16x32_bf16 v[64:67], v[182:185], v[222:225], v[64:67]
	s_barrier
	s_add_i32 s38, s39, s75
	v_lshl_add_u64 v[144:145], s[68:69], 0, v[96:97]
	s_mov_b32 m0, s38
	ds_read_b128 v[186:189], v152 offset:16384
	ds_read_b128 v[190:193], v152 offset:17408
	ds_read_b128 v[194:197], v152 offset:18432
	ds_read_b128 v[202:205], v152 offset:19456
	ds_read_b128 v[210:213], v152 offset:20480
	ds_read_b128 v[214:217], v152 offset:21504
	ds_read_b128 v[218:221], v152 offset:22528
	ds_read_b128 v[222:225], v152 offset:23552
	global_load_lds_dwordx4 v[144:145], off
	s_add_i32 m0, s38, 0x2000
	s_add_u32 s38, s68, 0x80000
	v_lshl_add_u64 v[198:199], s[68:69], 0, v[134:135]
	s_addc_u32 s39, s69, 0
	s_add_i32 s33, s33, s75
	global_load_lds_dwordx4 v[198:199], off
	v_lshl_add_u64 v[226:227], s[38:39], 0, v[96:97]
	s_mov_b32 m0, s33
	v_lshl_add_u64 v[228:229], s[82:83], 0, v[136:137]
	global_load_lds_dwordx4 v[226:227], off
	v_lshl_add_u64 v[226:227], s[38:39], 0, v[134:135]
	s_add_i32 m0, s33, 0x2000
	s_nop 0
	global_load_lds_dwordx4 v[226:227], off
	v_lshl_add_u64 v[226:227], s[82:83], 0, v[138:139]
	s_mov_b32 m0, s34
	s_nop 0
	global_load_lds_dwordx4 v[226:227], off
	s_mov_b32 m0, s35
	s_nop 0
	global_load_lds_dwordx4 v[228:229], off
	v_cmp_ne_u32_e32 vcc, 0, v243
	s_cbranch_vccnz .Lrx_G_UP_1
	s_waitcnt vmcnt(8)
.Lrx_G_UP_1:
	s_waitcnt vmcnt(24)
	v_mov_b32_e32 v243, 0
	s_waitcnt lgkmcnt(0)
	s_setprio 1
	s_barrier
	v_mfma_f32_16x16x32_bf16 v[60:63], v[154:157], v[186:189], v[60:63]
	v_mfma_f32_16x16x32_bf16 v[56:59], v[162:165], v[186:189], v[56:59]
	v_mfma_f32_16x16x32_bf16 v[44:47], v[154:157], v[194:197], v[44:47]
	v_mfma_f32_16x16x32_bf16 v[40:43], v[162:165], v[194:197], v[40:43]
	v_mfma_f32_16x16x32_bf16 v[28:31], v[154:157], v[210:213], v[28:31]
	v_mfma_f32_16x16x32_bf16 v[24:27], v[162:165], v[210:213], v[24:27]
	v_mfma_f32_16x16x32_bf16 v[12:15], v[154:157], v[218:221], v[12:15]
	v_mfma_f32_16x16x32_bf16 v[8:11], v[162:165], v[218:221], v[8:11]
	v_mfma_f32_16x16x32_bf16 v[60:63], v[158:161], v[190:193], v[60:63]
	v_mfma_f32_16x16x32_bf16 v[56:59], v[166:169], v[190:193], v[56:59]
	v_mfma_f32_16x16x32_bf16 v[44:47], v[158:161], v[202:205], v[44:47]
	v_mfma_f32_16x16x32_bf16 v[40:43], v[166:169], v[202:205], v[40:43]
	v_mfma_f32_16x16x32_bf16 v[28:31], v[158:161], v[214:217], v[28:31]
	v_mfma_f32_16x16x32_bf16 v[24:27], v[166:169], v[214:217], v[24:27]
	v_mfma_f32_16x16x32_bf16 v[12:15], v[158:161], v[222:225], v[12:15]
	v_mfma_f32_16x16x32_bf16 v[8:11], v[166:169], v[222:225], v[8:11]
	v_mfma_f32_16x16x32_bf16 v[52:55], v[170:173], v[186:189], v[52:55]
	v_mfma_f32_16x16x32_bf16 v[48:51], v[178:181], v[186:189], v[48:51]
	v_mfma_f32_16x16x32_bf16 v[36:39], v[170:173], v[194:197], v[36:39]
	v_mfma_f32_16x16x32_bf16 v[32:35], v[178:181], v[194:197], v[32:35]
	v_mfma_f32_16x16x32_bf16 v[20:23], v[170:173], v[210:213], v[20:23]
	v_mfma_f32_16x16x32_bf16 v[16:19], v[178:181], v[210:213], v[16:19]
	v_mfma_f32_16x16x32_bf16 v[4:7], v[170:173], v[218:221], v[4:7]
	v_mfma_f32_16x16x32_bf16 v[0:3], v[178:181], v[218:221], v[0:3]
	v_mfma_f32_16x16x32_bf16 v[52:55], v[174:177], v[190:193], v[52:55]
	v_mfma_f32_16x16x32_bf16 v[48:51], v[182:185], v[190:193], v[48:51]
	v_mfma_f32_16x16x32_bf16 v[36:39], v[174:177], v[202:205], v[36:39]
	v_mfma_f32_16x16x32_bf16 v[32:35], v[182:185], v[202:205], v[32:35]
	s_setprio 0
	v_mfma_f32_16x16x32_bf16 v[20:23], v[174:177], v[214:217], v[20:23]
	v_mfma_f32_16x16x32_bf16 v[16:19], v[182:185], v[214:217], v[16:19]
	v_mfma_f32_16x16x32_bf16 v[4:7], v[174:177], v[222:225], v[4:7]
	v_mfma_f32_16x16x32_bf16 v[0:3], v[182:185], v[222:225], v[0:3]
	s_barrier
	s_add_i32 s33, 0, 0x18000
	v_add_u32_e32 v153, s33, v150
	s_add_i32 s54, 0, 0x1c000
	ds_read_b128 v[154:157], v153
	ds_read_b128 v[158:161], v153 offset:1024
	ds_read_b128 v[162:165], v153 offset:2048
	ds_read_b128 v[166:169], v153 offset:3072
	v_add_u32_e32 v153, s54, v150
	ds_read_b128 v[170:173], v153
	ds_read_b128 v[174:177], v153 offset:1024
	ds_read_b128 v[178:181], v153 offset:2048
	ds_read_b128 v[182:185], v153 offset:3072
	s_add_u32 s38, s82, 0x80000
	s_addc_u32 s39, s83, 0
	s_mov_b32 m0, s50
	v_lshl_add_u64 v[230:231], s[38:39], 0, v[138:139]
	ds_read_b128 v[186:189], v152 offset:32768
	ds_read_b128 v[190:193], v152 offset:33792
	ds_read_b128 v[194:197], v152 offset:34816
	ds_read_b128 v[202:205], v152 offset:35840
	ds_read_b128 v[210:213], v152 offset:36864
	ds_read_b128 v[214:217], v152 offset:37888
	ds_read_b128 v[218:221], v152 offset:38912
	ds_read_b128 v[222:225], v152 offset:39936
	global_load_lds_dwordx4 v[230:231], off
	v_lshl_add_u64 v[230:231], s[38:39], 0, v[136:137]
	s_mov_b32 m0, s51
	s_nop 0
	global_load_lds_dwordx4 v[230:231], off
	s_waitcnt vmcnt(8)
	s_waitcnt lgkmcnt(0)
	s_setprio 1
	s_barrier
	v_mfma_f32_16x16x32_bf16 v[126:129], v[154:157], v[186:189], v[126:129]
	v_mfma_f32_16x16x32_bf16 v[122:125], v[162:165], v[186:189], v[122:125]
	v_mfma_f32_16x16x32_bf16 v[110:113], v[154:157], v[194:197], v[110:113]
	v_mfma_f32_16x16x32_bf16 v[106:109], v[162:165], v[194:197], v[106:109]
	v_mfma_f32_16x16x32_bf16 v[92:95], v[154:157], v[210:213], v[92:95]
	v_mfma_f32_16x16x32_bf16 v[88:91], v[162:165], v[210:213], v[88:91]
	v_mfma_f32_16x16x32_bf16 v[76:79], v[154:157], v[218:221], v[76:79]
	v_mfma_f32_16x16x32_bf16 v[72:75], v[162:165], v[218:221], v[72:75]
	v_mfma_f32_16x16x32_bf16 v[126:129], v[158:161], v[190:193], v[126:129]
	v_mfma_f32_16x16x32_bf16 v[122:125], v[166:169], v[190:193], v[122:125]
	v_mfma_f32_16x16x32_bf16 v[110:113], v[158:161], v[202:205], v[110:113]
	v_mfma_f32_16x16x32_bf16 v[106:109], v[166:169], v[202:205], v[106:109]
	v_mfma_f32_16x16x32_bf16 v[92:95], v[158:161], v[214:217], v[92:95]
	v_mfma_f32_16x16x32_bf16 v[88:91], v[166:169], v[214:217], v[88:91]
	v_mfma_f32_16x16x32_bf16 v[76:79], v[158:161], v[222:225], v[76:79]
	v_mfma_f32_16x16x32_bf16 v[72:75], v[166:169], v[222:225], v[72:75]
	v_mfma_f32_16x16x32_bf16 v[118:121], v[170:173], v[186:189], v[118:121]
	v_mfma_f32_16x16x32_bf16 v[114:117], v[178:181], v[186:189], v[114:117]
	v_mfma_f32_16x16x32_bf16 v[102:105], v[170:173], v[194:197], v[102:105]
	v_mfma_f32_16x16x32_bf16 v[98:101], v[178:181], v[194:197], v[98:101]
	v_mfma_f32_16x16x32_bf16 v[84:87], v[170:173], v[210:213], v[84:87]
	v_mfma_f32_16x16x32_bf16 v[80:83], v[178:181], v[210:213], v[80:83]
	v_mfma_f32_16x16x32_bf16 v[68:71], v[170:173], v[218:221], v[68:71]
	v_mfma_f32_16x16x32_bf16 v[64:67], v[178:181], v[218:221], v[64:67]
	v_mfma_f32_16x16x32_bf16 v[118:121], v[174:177], v[190:193], v[118:121]
	v_mfma_f32_16x16x32_bf16 v[114:117], v[182:185], v[190:193], v[114:117]
	v_mfma_f32_16x16x32_bf16 v[102:105], v[174:177], v[202:205], v[102:105]
	v_mfma_f32_16x16x32_bf16 v[98:101], v[182:185], v[202:205], v[98:101]
	s_setprio 0
	v_mfma_f32_16x16x32_bf16 v[84:87], v[174:177], v[214:217], v[84:87]
	v_mfma_f32_16x16x32_bf16 v[80:83], v[182:185], v[214:217], v[80:83]
	v_mfma_f32_16x16x32_bf16 v[68:71], v[174:177], v[222:225], v[68:71]
	v_mfma_f32_16x16x32_bf16 v[64:67], v[182:185], v[222:225], v[64:67]
	s_barrier
	s_add_i32 s33, s33, s75
	v_lshl_add_u64 v[144:145], v[144:145], 0, s[64:65]
	s_mov_b32 m0, s33
	ds_read_b128 v[186:189], v152 offset:49152
	ds_read_b128 v[190:193], v152 offset:50176
	ds_read_b128 v[194:197], v152 offset:51200
	ds_read_b128 v[202:205], v152 offset:52224
	ds_read_b128 v[210:213], v152 offset:53248
	ds_read_b128 v[214:217], v152 offset:54272
	ds_read_b128 v[218:221], v152 offset:55296
	ds_read_b128 v[222:225], v152 offset:56320
	global_load_lds_dwordx4 v[144:145], off
	s_add_i32 m0, s33, 0x2000
	s_add_u32 s38, s68, 0x80080
	v_lshl_add_u64 v[144:145], v[198:199], 0, s[64:65]
	s_addc_u32 s39, s69, 0
	s_add_i32 s33, s54, s75
	global_load_lds_dwordx4 v[144:145], off
	v_lshl_add_u64 v[144:145], s[38:39], 0, v[96:97]
	s_mov_b32 m0, s33
	s_nop 0
	global_load_lds_dwordx4 v[144:145], off
	v_lshl_add_u64 v[144:145], s[38:39], 0, v[134:135]
	s_add_i32 m0, s33, 0x2000
	s_nop 0
	global_load_lds_dwordx4 v[144:145], off
	v_lshl_add_u64 v[144:145], v[226:227], 0, s[64:65]
	s_mov_b32 m0, s58
	s_nop 0
	global_load_lds_dwordx4 v[144:145], off
	v_lshl_add_u64 v[144:145], v[228:229], 0, s[64:65]
	s_mov_b32 m0, s59
	s_nop 0
	global_load_lds_dwordx4 v[144:145], off
	s_waitcnt vmcnt(8)
	s_waitcnt lgkmcnt(0)
	s_setprio 1
	s_barrier
	v_mfma_f32_16x16x32_bf16 v[60:63], v[154:157], v[186:189], v[60:63]
	v_mfma_f32_16x16x32_bf16 v[56:59], v[162:165], v[186:189], v[56:59]
	v_mfma_f32_16x16x32_bf16 v[44:47], v[154:157], v[194:197], v[44:47]
	v_mfma_f32_16x16x32_bf16 v[40:43], v[162:165], v[194:197], v[40:43]
	v_mfma_f32_16x16x32_bf16 v[28:31], v[154:157], v[210:213], v[28:31]
	v_mfma_f32_16x16x32_bf16 v[24:27], v[162:165], v[210:213], v[24:27]
	v_mfma_f32_16x16x32_bf16 v[12:15], v[154:157], v[218:221], v[12:15]
	v_mfma_f32_16x16x32_bf16 v[8:11], v[162:165], v[218:221], v[8:11]
	v_mfma_f32_16x16x32_bf16 v[60:63], v[158:161], v[190:193], v[60:63]
	v_mfma_f32_16x16x32_bf16 v[56:59], v[166:169], v[190:193], v[56:59]
	v_mfma_f32_16x16x32_bf16 v[44:47], v[158:161], v[202:205], v[44:47]
	v_mfma_f32_16x16x32_bf16 v[40:43], v[166:169], v[202:205], v[40:43]
	v_mfma_f32_16x16x32_bf16 v[28:31], v[158:161], v[214:217], v[28:31]
	v_mfma_f32_16x16x32_bf16 v[24:27], v[166:169], v[214:217], v[24:27]
	v_mfma_f32_16x16x32_bf16 v[12:15], v[158:161], v[222:225], v[12:15]
	v_mfma_f32_16x16x32_bf16 v[8:11], v[166:169], v[222:225], v[8:11]
	v_mfma_f32_16x16x32_bf16 v[52:55], v[170:173], v[186:189], v[52:55]
	v_mfma_f32_16x16x32_bf16 v[48:51], v[178:181], v[186:189], v[48:51]
	v_mfma_f32_16x16x32_bf16 v[36:39], v[170:173], v[194:197], v[36:39]
	v_mfma_f32_16x16x32_bf16 v[32:35], v[178:181], v[194:197], v[32:35]
	v_mfma_f32_16x16x32_bf16 v[20:23], v[170:173], v[210:213], v[20:23]
	v_mfma_f32_16x16x32_bf16 v[16:19], v[178:181], v[210:213], v[16:19]
	v_mfma_f32_16x16x32_bf16 v[4:7], v[170:173], v[218:221], v[4:7]
	v_mfma_f32_16x16x32_bf16 v[0:3], v[178:181], v[218:221], v[0:3]
	v_mfma_f32_16x16x32_bf16 v[52:55], v[174:177], v[190:193], v[52:55]
	v_mfma_f32_16x16x32_bf16 v[48:51], v[182:185], v[190:193], v[48:51]
	v_mfma_f32_16x16x32_bf16 v[36:39], v[174:177], v[202:205], v[36:39]
	v_mfma_f32_16x16x32_bf16 v[32:35], v[182:185], v[202:205], v[32:35]
	s_setprio 0
	v_mfma_f32_16x16x32_bf16 v[20:23], v[174:177], v[214:217], v[20:23]
	v_mfma_f32_16x16x32_bf16 v[16:19], v[182:185], v[214:217], v[16:19]
	v_mfma_f32_16x16x32_bf16 v[4:7], v[174:177], v[222:225], v[4:7]
	v_mfma_f32_16x16x32_bf16 v[0:3], v[182:185], v[222:225], v[0:3]
	s_barrier
	s_add_i32 s28, s28, 2
	s_add_u32 s52, s52, 0x100
	s_addc_u32 s53, s53, 0
	s_add_u32 s20, s20, 0x100
	s_addc_u32 s25, s25, 0
	s_cmp_gt_u32 s28, 29
	s_cbranch_scc0 .LBB0_1284
	v_mov_b32_e32 v243, 1
	v_readlane_b32 s6, v251, 54
	v_readlane_b32 s7, v251, 55
	s_and_b64 vcc, exec, s[6:7]
	s_cbranch_vccz .LBB0_1287
	s_barrier
